# s15 + GEMM loops G1a/G1b/G3: first K-loop iteration peeled with srcC=0 on each accumulator's first MFMA; the 128 v_mov zeroing instructions per unit removed
# baseline (speedup 1.0000x reference)
; #define PG8_STAGE(bufoff, gbase, voff) do { _Pragma("unroll") for (int _i = 0; _i < 2; ++_i) \
;         __builtin_amdgcn_global_load_lds((const unsigned*)((const char*)(gbase) + (voff)[_i]), (PG8_LAS unsigned*)(lds + (bufoff) + ldsw + _i * 8192), 16, 0, 0); } while (0)
; #define PG8_LDA(dst, b, h) do { _Pragma("unroll") for (int m = 0; m < 4; ++m) _Pragma("unroll") for (int k = 0; k < 2; ++k) dst[m][k] = *(const PG8_LAS bf16x8*)(lds + PG8_SA(b, h) + aoff + m * 2048 + k * 1024); } while (0)
; #define PG8_LDB(dst, b, h) do { _Pragma("unroll") for (int n = 0; n < 2; ++n) _Pragma("unroll") for (int k = 0; k < 2; ++k) dst[n][k] = *(const PG8_LAS bf16x8*)(lds + PG8_SB(b, h) + boff + n * 2048 + k * 1024); } while (0)
; template <class Epi, class Sched, bool ALIGN_EPI = false, bool SP2 = false, bool I8 = false>
; __device__ __forceinline__ void gemm_phase(PG8_LAS unsigned char* lds, const Gemm g, const Sched& S, const Epi& E, const int tid) {
;     ...
;         const bool has_next = S.next(ui + 1, nxt);
;         const char* nA = has_next ? (const char*)g.A + (size_t)nxt.pm * tstepA : cA; const char* nB = has_next ? (const char*)g.Bt + (size_t)nxt.pn * tstepB : cB;
;         for (int t = 0; t < nt; t += 2) {
;             const bool last = (t == nt - 2);
;             const char* a1 = cA + (size_t)(t + 1) * kstep;
;             const char* a2 = last ? nA : cA + (size_t)(t + 2) * kstep; const char* b2 = last ? nB : cB + (size_t)(t + 2) * kstep;
;             const char* a3 = a2 + kstep; const char* b3 = b2 + kstep;
;             if (last && has_next) S.a_ready(nxt);
;             if constexpr (SP2) {
;             PG8_LDB(B0, 0, 0); PG8_LDB(B1, 0, 1); PG8_SCHED; PG8_LDA(At, 0, 0); PG8_STAGE(PG8_SA(1, 1), a1 + hstepA, voffA);
;             PG8_WAIT_V(8); PG8_WAIT_L(0); PG8_BAR; PG8_MMA(0, 0, At, B0); PG8_MMA(0, 1, At, B1); PG8_BAR; PG8_SCHED;
;             PG8_LDA(At, 0, 1); PG8_STAGE(PG8_SB(0, 0), b2, voffB); PG8_STAGE(PG8_SB(0, 1), b2 + hstepB, voffB); PG8_STAGE(PG8_SA(0, 0), a2, voffA);
;             PG8_WAIT_V(8); PG8_WAIT_L(0); PG8_BAR; PG8_MMA(1, 0, At, B0); PG8_MMA(1, 1, At, B1); PG8_BAR; PG8_SCHED;
;     ...
;         for (int a = 0; a < 2; ++a)
; #pragma unroll
;             for (int b = 0; b < 2; ++b)
; #pragma unroll
;                 for (int m = 0; m < 4; ++m)
; #pragma unroll
;                     for (int n = 0; n < 2; ++n) acc[a][b][m][n] = AccT<I8>::zero();
.LBB0_269:
	s_ashr_i32 s29, s28, 31
	s_lshl_b64 s[30:31], s[28:29], 21
	s_add_u32 s30, s57, s30
	s_addc_u32 s31, s58, s31
	s_and_b64 s[36:37], s[34:35], exec
	s_cselect_b32 s11, s31, s41
	s_cselect_b32 s29, s30, s40
	s_ashr_i32 s27, s26, 31
	s_lshl_b64 s[36:37], s[26:27], 21
	s_add_u32 s36, s5, s36
	s_addc_u32 s37, s56, s37
	s_and_b64 s[46:47], s[34:35], exec
	s_cselect_b32 s27, s37, s39
	s_cselect_b32 s80, s36, s38
	s_add_u32 s85, s38, 0x100
	s_addc_u32 s86, s39, 0
	s_add_u32 s38, s40, 0x100080
	s_addc_u32 s39, s41, 0
	s_mov_b32 s87, -2
	s_add_u32 s40, s38, 0xfff00080
	s_addc_u32 s41, s39, -1
	s_add_i32 s88, 0, 0x10000
	s_cmp_eq_u32 s87, 60
	s_cselect_b32 s47, s11, s41
	s_cselect_b32 s46, s29, s40
	s_cselect_b32 s41, s27, s86
	s_cselect_b32 s40, s80, s85
	s_add_i32 s90, 0, 0x14000
	v_add_u32_e32 v156, s88, v141
	v_add_u32_e32 v172, s90, v141
	ds_read_b128 v[144:147], v156
	ds_read_b128 v[148:151], v156 offset:1024
	ds_read_b128 v[152:155], v156 offset:2048
	ds_read_b128 v[156:159], v156 offset:3072
	ds_read_b128 v[160:163], v172
	ds_read_b128 v[164:167], v172 offset:1024
	ds_read_b128 v[168:171], v172 offset:2048
	ds_read_b128 v[172:175], v172 offset:3072
	v_lshl_add_u64 v[212:213], s[38:39], 0, v[138:139]
	s_add_i32 m0, s13, 0xc000
	ds_read_b128 v[176:179], v143
	ds_read_b128 v[180:183], v143 offset:1024
	ds_read_b128 v[184:187], v143 offset:2048
	ds_read_b128 v[188:191], v143 offset:3072
	ds_read_b128 v[192:195], v143 offset:4096
	ds_read_b128 v[200:203], v143 offset:5120
	ds_read_b128 v[204:207], v143 offset:6144
	ds_read_b128 v[208:211], v143 offset:7168
	global_load_lds_dwordx4 v[212:213], off
	v_lshl_add_u64 v[212:213], s[38:39], 0, v[136:137]
	s_add_i32 m0, s13, 0xe000
	s_nop 0
	global_load_lds_dwordx4 v[212:213], off
	s_waitcnt vmcnt(8)
	s_waitcnt lgkmcnt(0)
	s_barrier
	s_setprio 1
	s_waitcnt lgkmcnt(0)
	v_mfma_f32_16x16x32_bf16 v[126:129], v[144:147], v[176:179], 0
	v_mfma_f32_16x16x32_bf16 v[122:125], v[152:155], v[176:179], 0
	v_mfma_f32_16x16x32_bf16 v[118:121], v[144:147], v[184:187], 0
	v_mfma_f32_16x16x32_bf16 v[114:117], v[152:155], v[184:187], 0
	v_mfma_f32_16x16x32_bf16 v[102:105], v[144:147], v[192:195], 0
	v_mfma_f32_16x16x32_bf16 v[98:101], v[152:155], v[192:195], 0
	v_mfma_f32_16x16x32_bf16 v[84:87], v[144:147], v[204:207], 0
	v_mfma_f32_16x16x32_bf16 v[80:83], v[152:155], v[204:207], 0
	v_mfma_f32_16x16x32_bf16 v[126:129], v[148:151], v[180:183], v[126:129]
	v_mfma_f32_16x16x32_bf16 v[122:125], v[156:159], v[180:183], v[122:125]
	v_mfma_f32_16x16x32_bf16 v[118:121], v[148:151], v[188:191], v[118:121]
	v_mfma_f32_16x16x32_bf16 v[114:117], v[156:159], v[188:191], v[114:117]
	v_mfma_f32_16x16x32_bf16 v[102:105], v[148:151], v[200:203], v[102:105]
	v_mfma_f32_16x16x32_bf16 v[98:101], v[156:159], v[200:203], v[98:101]
	v_mfma_f32_16x16x32_bf16 v[84:87], v[148:151], v[208:211], v[84:87]
	v_mfma_f32_16x16x32_bf16 v[80:83], v[156:159], v[208:211], v[80:83]
	s_setprio 0
	s_setprio 1
	v_mfma_f32_16x16x32_bf16 v[110:113], v[160:163], v[176:179], 0
	v_mfma_f32_16x16x32_bf16 v[106:109], v[168:171], v[176:179], 0
	v_mfma_f32_16x16x32_bf16 v[92:95], v[160:163], v[184:187], 0
	v_mfma_f32_16x16x32_bf16 v[88:91], v[168:171], v[184:187], 0
	v_mfma_f32_16x16x32_bf16 v[76:79], v[160:163], v[192:195], 0
	v_mfma_f32_16x16x32_bf16 v[72:75], v[168:171], v[192:195], 0
	v_mfma_f32_16x16x32_bf16 v[68:71], v[160:163], v[204:207], 0
	v_mfma_f32_16x16x32_bf16 v[64:67], v[168:171], v[204:207], 0
	v_mfma_f32_16x16x32_bf16 v[110:113], v[164:167], v[180:183], v[110:113]
	v_mfma_f32_16x16x32_bf16 v[106:109], v[172:175], v[180:183], v[106:109]
	v_mfma_f32_16x16x32_bf16 v[92:95], v[164:167], v[188:191], v[92:95]
	v_mfma_f32_16x16x32_bf16 v[88:91], v[172:175], v[188:191], v[88:91]
	v_mfma_f32_16x16x32_bf16 v[76:79], v[164:167], v[200:203], v[76:79]
	v_mfma_f32_16x16x32_bf16 v[72:75], v[172:175], v[200:203], v[72:75]
	v_mfma_f32_16x16x32_bf16 v[68:71], v[164:167], v[208:211], v[68:71]
	v_mfma_f32_16x16x32_bf16 v[64:67], v[172:175], v[208:211], v[64:67]
	s_setprio 0
	s_barrier
	s_add_i32 s88, s88, s59
	v_lshl_add_u64 v[212:213], s[40:41], 0, v[96:97]
	s_mov_b32 m0, s88
	ds_read_b128 v[176:179], v143 offset:16384
	ds_read_b128 v[180:183], v143 offset:17408
	ds_read_b128 v[184:187], v143 offset:18432
	ds_read_b128 v[188:191], v143 offset:19456
	ds_read_b128 v[192:195], v143 offset:20480
	ds_read_b128 v[200:203], v143 offset:21504
	ds_read_b128 v[204:207], v143 offset:22528
	ds_read_b128 v[208:211], v143 offset:23552
	global_load_lds_dwordx4 v[212:213], off
	s_add_i32 m0, s88, 0x2000
	s_add_u32 s88, s40, 0x100000
	v_lshl_add_u64 v[214:215], s[40:41], 0, v[134:135]
	s_addc_u32 s89, s41, 0
	s_add_i32 s90, s90, s59
	global_load_lds_dwordx4 v[214:215], off
	v_lshl_add_u64 v[216:217], s[88:89], 0, v[96:97]
	s_mov_b32 m0, s90
	v_lshl_add_u64 v[218:219], s[46:47], 0, v[132:133]
	global_load_lds_dwordx4 v[216:217], off
	v_lshl_add_u64 v[216:217], s[88:89], 0, v[134:135]
	s_add_i32 m0, s90, 0x2000
	s_nop 0
	global_load_lds_dwordx4 v[216:217], off
	v_lshl_add_u64 v[216:217], s[46:47], 0, v[130:131]
	s_mov_b32 m0, s13
	s_nop 0
	global_load_lds_dwordx4 v[216:217], off
	s_mov_b32 m0, s60
	s_nop 0
	global_load_lds_dwordx4 v[218:219], off
	s_waitcnt vmcnt(8)
	s_waitcnt lgkmcnt(0)
	s_barrier
; #define PG8_STAGE(bufoff, gbase, voff) do { _Pragma("unroll") for (int _i = 0; _i < 2; ++_i) \
;         __builtin_amdgcn_global_load_lds((const unsigned*)((const char*)(gbase) + (voff)[_i]), (PG8_LAS unsigned*)(lds + (bufoff) + ldsw + _i * 8192), 16, 0, 0); } while (0)
; #define PG8_LDA(dst, b, h) do { _Pragma("unroll") for (int m = 0; m < 4; ++m) _Pragma("unroll") for (int k = 0; k < 2; ++k) dst[m][k] = *(const PG8_LAS bf16x8*)(lds + PG8_SA(b, h) + aoff + m * 2048 + k * 1024); } while (0)
; #define PG8_LDB(dst, b, h) do { _Pragma("unroll") for (int n = 0; n < 2; ++n) _Pragma("unroll") for (int k = 0; k < 2; ++k) dst[n][k] = *(const PG8_LAS bf16x8*)(lds + PG8_SB(b, h) + boff + n * 2048 + k * 1024); } while (0)
; #define PG8_MMA(ai, bj, At, Bt) do { __builtin_amdgcn_s_setprio(1); _Pragma("unroll") for (int m = 0; m < 4; ++m) _Pragma("unroll") for (int n = 0; n < 2; ++n) _Pragma("unroll") for (int k = 0; k < 2; ++k) \
;         mma1<I8>(acc[ai][bj][m][n], Bt[n][k], At[m][k]); __builtin_amdgcn_s_setprio(0); } while (0)
; #define PG8_WAIT_V(n) asm volatile("s_waitcnt vmcnt(" #n ")" ::: "memory")
; #define PG8_WAIT_L(n) asm volatile("s_waitcnt lgkmcnt(" #n ")" ::: "memory")
; #define PG8_BAR __builtin_amdgcn_s_barrier()
; #define PG8_SCHED __builtin_amdgcn_sched_barrier(0)
; template <class Epi, class Sched, bool ALIGN_EPI = false, bool SP2 = false, bool I8 = false>
; __device__ __forceinline__ void gemm_phase(PG8_LAS unsigned char* lds, const Gemm g, const Sched& S, const Epi& E, const int tid) {
;     ...
;             PG8_WAIT_V(8); PG8_WAIT_L(0); PG8_BAR; PG8_MMA(1, 0, At, B0); PG8_MMA(1, 1, At, B1); PG8_BAR; PG8_SCHED;
;             PG8_LDB(B0, 1, 0); PG8_LDB(B1, 1, 1); PG8_SCHED; PG8_LDA(At, 1, 0); PG8_STAGE(PG8_SA(0, 1), a2 + hstepA, voffA);
;             PG8_WAIT_V(8); PG8_WAIT_L(0); PG8_BAR; PG8_MMA(0, 0, At, B0); PG8_MMA(0, 1, At, B1); PG8_BAR; PG8_SCHED;
	s_setprio 1
	s_waitcnt lgkmcnt(0)
	v_mfma_f32_16x16x32_bf16 v[60:63], v[144:147], v[176:179], 0
	v_mfma_f32_16x16x32_bf16 v[56:59], v[152:155], v[176:179], 0
	v_mfma_f32_16x16x32_bf16 v[52:55], v[144:147], v[184:187], 0
	v_mfma_f32_16x16x32_bf16 v[48:51], v[152:155], v[184:187], 0
	v_mfma_f32_16x16x32_bf16 v[36:39], v[144:147], v[192:195], 0
	v_mfma_f32_16x16x32_bf16 v[32:35], v[152:155], v[192:195], 0
	v_mfma_f32_16x16x32_bf16 v[20:23], v[144:147], v[204:207], 0
	v_mfma_f32_16x16x32_bf16 v[16:19], v[152:155], v[204:207], 0
	v_mfma_f32_16x16x32_bf16 v[60:63], v[148:151], v[180:183], v[60:63]
	v_mfma_f32_16x16x32_bf16 v[56:59], v[156:159], v[180:183], v[56:59]
	v_mfma_f32_16x16x32_bf16 v[52:55], v[148:151], v[188:191], v[52:55]
	v_mfma_f32_16x16x32_bf16 v[48:51], v[156:159], v[188:191], v[48:51]
	v_mfma_f32_16x16x32_bf16 v[36:39], v[148:151], v[200:203], v[36:39]
	v_mfma_f32_16x16x32_bf16 v[32:35], v[156:159], v[200:203], v[32:35]
	v_mfma_f32_16x16x32_bf16 v[20:23], v[148:151], v[208:211], v[20:23]
	v_mfma_f32_16x16x32_bf16 v[16:19], v[156:159], v[208:211], v[16:19]
	s_setprio 0
	s_setprio 1
	v_mfma_f32_16x16x32_bf16 v[44:47], v[160:163], v[176:179], 0
	v_mfma_f32_16x16x32_bf16 v[40:43], v[168:171], v[176:179], 0
	v_mfma_f32_16x16x32_bf16 v[28:31], v[160:163], v[184:187], 0
	v_mfma_f32_16x16x32_bf16 v[24:27], v[168:171], v[184:187], 0
	v_mfma_f32_16x16x32_bf16 v[12:15], v[160:163], v[192:195], 0
	v_mfma_f32_16x16x32_bf16 v[8:11], v[168:171], v[192:195], 0
	v_mfma_f32_16x16x32_bf16 v[4:7], v[160:163], v[204:207], 0
	v_mfma_f32_16x16x32_bf16 v[0:3], v[168:171], v[204:207], 0
	v_mfma_f32_16x16x32_bf16 v[44:47], v[164:167], v[180:183], v[44:47]
	v_mfma_f32_16x16x32_bf16 v[40:43], v[172:175], v[180:183], v[40:43]
	v_mfma_f32_16x16x32_bf16 v[28:31], v[164:167], v[188:191], v[28:31]
	v_mfma_f32_16x16x32_bf16 v[24:27], v[172:175], v[188:191], v[24:27]
	v_mfma_f32_16x16x32_bf16 v[12:15], v[164:167], v[200:203], v[12:15]
	v_mfma_f32_16x16x32_bf16 v[8:11], v[172:175], v[200:203], v[8:11]
	v_mfma_f32_16x16x32_bf16 v[4:7], v[164:167], v[208:211], v[4:7]
	v_mfma_f32_16x16x32_bf16 v[0:3], v[172:175], v[208:211], v[0:3]
	s_setprio 0
	s_barrier
	s_add_i32 s88, 0, 0x18000
	s_add_i32 s89, 0, 0x1c000
	v_add_u32_e32 v156, s88, v141
	v_add_u32_e32 v172, s89, v141
	ds_read_b128 v[144:147], v156
	ds_read_b128 v[148:151], v156 offset:1024
	ds_read_b128 v[152:155], v156 offset:2048
	ds_read_b128 v[156:159], v156 offset:3072
	ds_read_b128 v[160:163], v172
	ds_read_b128 v[164:167], v172 offset:1024
	ds_read_b128 v[168:171], v172 offset:2048
	ds_read_b128 v[172:175], v172 offset:3072
	s_add_u32 s46, s46, 0x100000
	s_addc_u32 s47, s47, 0
	s_mov_b32 m0, s62
	v_lshl_add_u64 v[220:221], s[46:47], 0, v[130:131]
	ds_read_b128 v[176:179], v143 offset:32768
	ds_read_b128 v[180:183], v143 offset:33792
	ds_read_b128 v[184:187], v143 offset:34816
	ds_read_b128 v[188:191], v143 offset:35840
	ds_read_b128 v[192:195], v143 offset:36864
	ds_read_b128 v[200:203], v143 offset:37888
	ds_read_b128 v[204:207], v143 offset:38912
	ds_read_b128 v[208:211], v143 offset:39936
	global_load_lds_dwordx4 v[220:221], off
	v_lshl_add_u64 v[220:221], s[46:47], 0, v[132:133]
	s_mov_b32 m0, s63
	s_nop 0
	global_load_lds_dwordx4 v[220:221], off
	s_waitcnt vmcnt(8)
	s_waitcnt lgkmcnt(0)
	s_barrier
	s_setprio 1
	s_waitcnt lgkmcnt(0)
	v_mfma_f32_16x16x32_bf16 v[126:129], v[144:147], v[176:179], v[126:129]
	v_mfma_f32_16x16x32_bf16 v[122:125], v[152:155], v[176:179], v[122:125]
	v_mfma_f32_16x16x32_bf16 v[118:121], v[144:147], v[184:187], v[118:121]
	v_mfma_f32_16x16x32_bf16 v[114:117], v[152:155], v[184:187], v[114:117]
	v_mfma_f32_16x16x32_bf16 v[102:105], v[144:147], v[192:195], v[102:105]
	v_mfma_f32_16x16x32_bf16 v[98:101], v[152:155], v[192:195], v[98:101]
	v_mfma_f32_16x16x32_bf16 v[84:87], v[144:147], v[204:207], v[84:87]
	v_mfma_f32_16x16x32_bf16 v[80:83], v[152:155], v[204:207], v[80:83]
	v_mfma_f32_16x16x32_bf16 v[126:129], v[148:151], v[180:183], v[126:129]
	v_mfma_f32_16x16x32_bf16 v[122:125], v[156:159], v[180:183], v[122:125]
	v_mfma_f32_16x16x32_bf16 v[118:121], v[148:151], v[188:191], v[118:121]
	v_mfma_f32_16x16x32_bf16 v[114:117], v[156:159], v[188:191], v[114:117]
	v_mfma_f32_16x16x32_bf16 v[102:105], v[148:151], v[200:203], v[102:105]
	v_mfma_f32_16x16x32_bf16 v[98:101], v[156:159], v[200:203], v[98:101]
	v_mfma_f32_16x16x32_bf16 v[84:87], v[148:151], v[208:211], v[84:87]
	v_mfma_f32_16x16x32_bf16 v[80:83], v[156:159], v[208:211], v[80:83]
	s_setprio 0
	s_setprio 1
	v_mfma_f32_16x16x32_bf16 v[110:113], v[160:163], v[176:179], v[110:113]
	v_mfma_f32_16x16x32_bf16 v[106:109], v[168:171], v[176:179], v[106:109]
	v_mfma_f32_16x16x32_bf16 v[92:95], v[160:163], v[184:187], v[92:95]
	v_mfma_f32_16x16x32_bf16 v[88:91], v[168:171], v[184:187], v[88:91]
	v_mfma_f32_16x16x32_bf16 v[76:79], v[160:163], v[192:195], v[76:79]
	v_mfma_f32_16x16x32_bf16 v[72:75], v[168:171], v[192:195], v[72:75]
	v_mfma_f32_16x16x32_bf16 v[68:71], v[160:163], v[204:207], v[68:71]
	v_mfma_f32_16x16x32_bf16 v[64:67], v[168:171], v[204:207], v[64:67]
	v_mfma_f32_16x16x32_bf16 v[110:113], v[164:167], v[180:183], v[110:113]
	v_mfma_f32_16x16x32_bf16 v[106:109], v[172:175], v[180:183], v[106:109]
	v_mfma_f32_16x16x32_bf16 v[92:95], v[164:167], v[188:191], v[92:95]
	v_mfma_f32_16x16x32_bf16 v[88:91], v[172:175], v[188:191], v[88:91]
	v_mfma_f32_16x16x32_bf16 v[76:79], v[164:167], v[200:203], v[76:79]
	v_mfma_f32_16x16x32_bf16 v[72:75], v[172:175], v[200:203], v[72:75]
	v_mfma_f32_16x16x32_bf16 v[68:71], v[164:167], v[208:211], v[68:71]
	v_mfma_f32_16x16x32_bf16 v[64:67], v[172:175], v[208:211], v[64:67]
	s_setprio 0
	s_barrier
; #define PG8_STAGE(bufoff, gbase, voff) do { _Pragma("unroll") for (int _i = 0; _i < 2; ++_i) \
;         __builtin_amdgcn_global_load_lds((const unsigned*)((const char*)(gbase) + (voff)[_i]), (PG8_LAS unsigned*)(lds + (bufoff) + ldsw + _i * 8192), 16, 0, 0); } while (0)
; #define PG8_LDA(dst, b, h) do { _Pragma("unroll") for (int m = 0; m < 4; ++m) _Pragma("unroll") for (int k = 0; k < 2; ++k) dst[m][k] = *(const PG8_LAS bf16x8*)(lds + PG8_SA(b, h) + aoff + m * 2048 + k * 1024); } while (0)
; #define PG8_MMA(ai, bj, At, Bt) do { __builtin_amdgcn_s_setprio(1); _Pragma("unroll") for (int m = 0; m < 4; ++m) _Pragma("unroll") for (int n = 0; n < 2; ++n) _Pragma("unroll") for (int k = 0; k < 2; ++k) \
;         mma1<I8>(acc[ai][bj][m][n], Bt[n][k], At[m][k]); __builtin_amdgcn_s_setprio(0); } while (0)
; #define PG8_WAIT_V(n) asm volatile("s_waitcnt vmcnt(" #n ")" ::: "memory")
; #define PG8_WAIT_L(n) asm volatile("s_waitcnt lgkmcnt(" #n ")" ::: "memory")
; #define PG8_BAR __builtin_amdgcn_s_barrier()
; #define PG8_SCHED __builtin_amdgcn_sched_barrier(0)
; template <class Epi, class Sched, bool ALIGN_EPI = false, bool SP2 = false, bool I8 = false>
; __device__ __forceinline__ void gemm_phase(PG8_LAS unsigned char* lds, const Gemm g, const Sched& S, const Epi& E, const int tid) {
;     ...
;         for (int t = 0; t < nt; t += 2) {
;     ...
;             PG8_LDA(At, 1, 1); PG8_STAGE(PG8_SB(1, 0), b3, voffB); PG8_STAGE(PG8_SB(1, 1), b3 + hstepB, voffB); PG8_STAGE(PG8_SA(1, 0), a3, voffA);
;             PG8_WAIT_V(8); PG8_WAIT_L(0); PG8_BAR; PG8_MMA(1, 0, At, B0); PG8_MMA(1, 1, At, B1); PG8_BAR; PG8_SCHED;
	s_add_i32 s46, s88, s59
	v_lshl_add_u64 v[212:213], v[212:213], 0, s[42:43]
	s_mov_b32 m0, s46
	ds_read_b128 v[176:179], v143 offset:49152
	ds_read_b128 v[180:183], v143 offset:50176
	ds_read_b128 v[184:187], v143 offset:51200
	ds_read_b128 v[188:191], v143 offset:52224
	ds_read_b128 v[192:195], v143 offset:53248
	ds_read_b128 v[200:203], v143 offset:54272
	ds_read_b128 v[204:207], v143 offset:55296
	ds_read_b128 v[208:211], v143 offset:56320
	global_load_lds_dwordx4 v[212:213], off
	s_add_i32 m0, s46, 0x2000
	s_add_u32 s40, s40, 0x100080
	v_lshl_add_u64 v[212:213], v[214:215], 0, s[42:43]
	s_addc_u32 s41, s41, 0
	s_add_i32 s46, s89, s59
	global_load_lds_dwordx4 v[212:213], off
	v_lshl_add_u64 v[212:213], s[40:41], 0, v[96:97]
	s_mov_b32 m0, s46
	s_nop 0
	global_load_lds_dwordx4 v[212:213], off
	v_lshl_add_u64 v[212:213], s[40:41], 0, v[134:135]
	s_add_i32 m0, s46, 0x2000
	s_nop 0
	global_load_lds_dwordx4 v[212:213], off
	v_lshl_add_u64 v[212:213], v[216:217], 0, s[42:43]
	s_mov_b32 m0, s65
	s_nop 0
	global_load_lds_dwordx4 v[212:213], off
	v_lshl_add_u64 v[212:213], v[218:219], 0, s[42:43]
	s_mov_b32 m0, s66
	s_nop 0
	global_load_lds_dwordx4 v[212:213], off
	s_waitcnt vmcnt(8)
	s_waitcnt lgkmcnt(0)
	s_barrier
	s_setprio 1
	s_waitcnt lgkmcnt(0)
	v_mfma_f32_16x16x32_bf16 v[60:63], v[144:147], v[176:179], v[60:63]
	v_mfma_f32_16x16x32_bf16 v[56:59], v[152:155], v[176:179], v[56:59]
	v_mfma_f32_16x16x32_bf16 v[52:55], v[144:147], v[184:187], v[52:55]
	v_mfma_f32_16x16x32_bf16 v[48:51], v[152:155], v[184:187], v[48:51]
	v_mfma_f32_16x16x32_bf16 v[36:39], v[144:147], v[192:195], v[36:39]
	v_mfma_f32_16x16x32_bf16 v[32:35], v[152:155], v[192:195], v[32:35]
	v_mfma_f32_16x16x32_bf16 v[20:23], v[144:147], v[204:207], v[20:23]
	v_mfma_f32_16x16x32_bf16 v[16:19], v[152:155], v[204:207], v[16:19]
	v_mfma_f32_16x16x32_bf16 v[60:63], v[148:151], v[180:183], v[60:63]
	v_mfma_f32_16x16x32_bf16 v[56:59], v[156:159], v[180:183], v[56:59]
	v_mfma_f32_16x16x32_bf16 v[52:55], v[148:151], v[188:191], v[52:55]
	v_mfma_f32_16x16x32_bf16 v[48:51], v[156:159], v[188:191], v[48:51]
	v_mfma_f32_16x16x32_bf16 v[36:39], v[148:151], v[200:203], v[36:39]
	v_mfma_f32_16x16x32_bf16 v[32:35], v[156:159], v[200:203], v[32:35]
	v_mfma_f32_16x16x32_bf16 v[20:23], v[148:151], v[208:211], v[20:23]
	v_mfma_f32_16x16x32_bf16 v[16:19], v[156:159], v[208:211], v[16:19]
	s_setprio 0
	s_setprio 1
	v_mfma_f32_16x16x32_bf16 v[44:47], v[160:163], v[176:179], v[44:47]
	v_mfma_f32_16x16x32_bf16 v[40:43], v[168:171], v[176:179], v[40:43]
	v_mfma_f32_16x16x32_bf16 v[28:31], v[160:163], v[184:187], v[28:31]
	v_mfma_f32_16x16x32_bf16 v[24:27], v[168:171], v[184:187], v[24:27]
	v_mfma_f32_16x16x32_bf16 v[12:15], v[160:163], v[192:195], v[12:15]
	v_mfma_f32_16x16x32_bf16 v[8:11], v[168:171], v[192:195], v[8:11]
	v_mfma_f32_16x16x32_bf16 v[4:7], v[160:163], v[204:207], v[4:7]
	v_mfma_f32_16x16x32_bf16 v[0:3], v[168:171], v[204:207], v[0:3]
	v_mfma_f32_16x16x32_bf16 v[44:47], v[164:167], v[180:183], v[44:47]
	v_mfma_f32_16x16x32_bf16 v[40:43], v[172:175], v[180:183], v[40:43]
	v_mfma_f32_16x16x32_bf16 v[28:31], v[164:167], v[188:191], v[28:31]
	v_mfma_f32_16x16x32_bf16 v[24:27], v[172:175], v[188:191], v[24:27]
	v_mfma_f32_16x16x32_bf16 v[12:15], v[164:167], v[200:203], v[12:15]
	v_mfma_f32_16x16x32_bf16 v[8:11], v[172:175], v[200:203], v[8:11]
	v_mfma_f32_16x16x32_bf16 v[4:7], v[164:167], v[208:211], v[4:7]
	v_mfma_f32_16x16x32_bf16 v[0:3], v[172:175], v[208:211], v[0:3]
	s_setprio 0
	s_barrier
	s_add_i32 s87, s87, 2
	s_add_u32 s85, s85, 0x100
	s_addc_u32 s86, s86, 0
	s_add_u32 s38, s38, 0x100
	s_addc_u32 s39, s39, 0
	s_cmp_gt_u32 s87, 61

; #define PG8_STAGE(bufoff, gbase, voff) do { _Pragma("unroll") for (int _i = 0; _i < 2; ++_i) \
;         __builtin_amdgcn_global_load_lds((const unsigned*)((const char*)(gbase) + (voff)[_i]), (PG8_LAS unsigned*)(lds + (bufoff) + ldsw + _i * 8192), 16, 0, 0); } while (0)
; #define PG8_LDA(dst, b, h) do { _Pragma("unroll") for (int m = 0; m < 4; ++m) _Pragma("unroll") for (int k = 0; k < 2; ++k) dst[m][k] = *(const PG8_LAS bf16x8*)(lds + PG8_SA(b, h) + aoff + m * 2048 + k * 1024); } while (0)
; #define PG8_LDB(dst, b, h) do { _Pragma("unroll") for (int n = 0; n < 2; ++n) _Pragma("unroll") for (int k = 0; k < 2; ++k) dst[n][k] = *(const PG8_LAS bf16x8*)(lds + PG8_SB(b, h) + boff + n * 2048 + k * 1024); } while (0)
; template <class Epi, class Sched, bool ALIGN_EPI = false, bool SP2 = false, bool I8 = false>
; __device__ __forceinline__ void gemm_phase(PG8_LAS unsigned char* lds, const Gemm g, const Sched& S, const Epi& E, const int tid) {
;     ...
;         const bool has_next = S.next(ui + 1, nxt);
;         const char* nA = has_next ? (const char*)g.A + (size_t)nxt.pm * tstepA : cA; const char* nB = has_next ? (const char*)g.Bt + (size_t)nxt.pn * tstepB : cB;
;         for (int t = 0; t < nt; t += 2) {
;             const bool last = (t == nt - 2);
;             const char* a1 = cA + (size_t)(t + 1) * kstep;
;             const char* a2 = last ? nA : cA + (size_t)(t + 2) * kstep; const char* b2 = last ? nB : cB + (size_t)(t + 2) * kstep;
;             const char* a3 = a2 + kstep; const char* b3 = b2 + kstep;
;             if (last && has_next) S.a_ready(nxt);
;             if constexpr (SP2) {
;             PG8_LDB(B0, 0, 0); PG8_LDB(B1, 0, 1); PG8_SCHED; PG8_LDA(At, 0, 0); PG8_STAGE(PG8_SA(1, 1), a1 + hstepA, voffA);
;             PG8_WAIT_V(8); PG8_WAIT_L(0); PG8_BAR; PG8_MMA(0, 0, At, B0); PG8_MMA(0, 1, At, B1); PG8_BAR; PG8_SCHED;
;             PG8_LDA(At, 0, 1); PG8_STAGE(PG8_SB(0, 0), b2, voffB); PG8_STAGE(PG8_SB(0, 1), b2 + hstepB, voffB); PG8_STAGE(PG8_SA(0, 0), a2, voffA);
;             PG8_WAIT_V(8); PG8_WAIT_L(0); PG8_BAR; PG8_MMA(1, 0, At, B0); PG8_MMA(1, 1, At, B1); PG8_BAR; PG8_SCHED;
;     ...
;         for (int a = 0; a < 2; ++a)
; #pragma unroll
;             for (int b = 0; b < 2; ++b)
; #pragma unroll
;                 for (int m = 0; m < 4; ++m)
; #pragma unroll
;                     for (int n = 0; n < 2; ++n) acc[a][b][m][n] = AccT<I8>::zero();
.LBB0_334:
	s_ashr_i32 s31, s30, 31
	s_lshl_b64 s[34:35], s[30:31], 20
	s_add_u32 s34, s73, s34
	s_addc_u32 s35, s74, s35
	s_and_b64 s[38:39], s[36:37], exec
	s_cselect_b32 s5, s35, s55
	s_cselect_b32 s31, s34, s54
	s_ashr_i32 s13, s12, 31
	s_lshl_b64 s[38:39], s[12:13], 20
	s_add_u32 s38, s9, s38
	s_addc_u32 s39, s66, s39
	s_and_b64 s[56:57], s[36:37], exec
	s_cselect_b32 s13, s39, s47
	s_cselect_b32 s41, s38, s46
	s_add_u32 s49, s46, 0x100
	s_addc_u32 s60, s47, 0
	s_add_u32 s46, s54, 0x80080
	s_addc_u32 s47, s55, 0
	s_mov_b32 s65, -2
	s_add_u32 s54, s46, 0xfff80080
	s_addc_u32 s55, s47, -1
	s_add_i32 s70, 0, 0x10000
	s_cmp_eq_u32 s65, 28
	s_cselect_b32 s57, s5, s55
	s_cselect_b32 s56, s31, s54
	s_cselect_b32 s55, s13, s60
	s_cselect_b32 s54, s41, s49
	s_add_i32 s87, 0, 0x14000
	v_add_u32_e32 v68, s70, v187
	v_add_u32_e32 v168, s87, v187
	ds_read_b128 v[48:51], v68
	ds_read_b128 v[52:55], v68 offset:1024
	ds_read_b128 v[64:67], v68 offset:2048
	ds_read_b128 v[68:71], v68 offset:3072
	ds_read_b128 v[156:159], v168
	ds_read_b128 v[160:163], v168 offset:1024
	ds_read_b128 v[164:167], v168 offset:2048
	ds_read_b128 v[168:171], v168 offset:3072
	v_lshl_add_u64 v[184:185], s[46:47], 0, v[154:155]
	s_add_i32 m0, s80, 0xc000
	ds_read_b128 v[172:175], v189
	ds_read_b128 v[176:179], v189 offset:1024
	ds_read_b128 v[180:183], v189 offset:2048
	ds_read_b128 v[190:193], v189 offset:3072
	ds_read_b128 v[200:203], v189 offset:4096
	ds_read_b128 v[204:207], v189 offset:5120
	ds_read_b128 v[208:211], v189 offset:6144
	ds_read_b128 v[212:215], v189 offset:7168
	global_load_lds_dwordx4 v[184:185], off
	v_lshl_add_u64 v[184:185], s[46:47], 0, v[152:153]
	s_add_i32 m0, s80, 0xe000
	s_nop 0
	global_load_lds_dwordx4 v[184:185], off
	s_waitcnt vmcnt(8)
	s_waitcnt lgkmcnt(0)
	s_barrier
	s_setprio 1
	s_waitcnt lgkmcnt(0)
	v_mfma_i32_16x16x64_i8 v[142:145], v[48:51], v[172:175], 0
	v_mfma_i32_16x16x64_i8 v[138:141], v[64:67], v[172:175], 0
	v_mfma_i32_16x16x64_i8 v[126:129], v[48:51], v[180:183], 0
	v_mfma_i32_16x16x64_i8 v[122:125], v[64:67], v[180:183], 0
	v_mfma_i32_16x16x64_i8 v[110:113], v[48:51], v[200:203], 0
	v_mfma_i32_16x16x64_i8 v[106:109], v[64:67], v[200:203], 0
	v_mfma_i32_16x16x64_i8 v[92:95], v[48:51], v[208:211], 0
	v_mfma_i32_16x16x64_i8 v[88:91], v[64:67], v[208:211], 0
	v_mfma_i32_16x16x64_i8 v[142:145], v[52:55], v[176:179], v[142:145]
	v_mfma_i32_16x16x64_i8 v[138:141], v[68:71], v[176:179], v[138:141]
	v_mfma_i32_16x16x64_i8 v[126:129], v[52:55], v[190:193], v[126:129]
	v_mfma_i32_16x16x64_i8 v[122:125], v[68:71], v[190:193], v[122:125]
	v_mfma_i32_16x16x64_i8 v[110:113], v[52:55], v[204:207], v[110:113]
	v_mfma_i32_16x16x64_i8 v[106:109], v[68:71], v[204:207], v[106:109]
	v_mfma_i32_16x16x64_i8 v[92:95], v[52:55], v[212:215], v[92:95]
	v_mfma_i32_16x16x64_i8 v[88:91], v[68:71], v[212:215], v[88:91]
	s_setprio 0
	s_setprio 1
	v_mfma_i32_16x16x64_i8 v[134:137], v[156:159], v[172:175], 0
	v_mfma_i32_16x16x64_i8 v[130:133], v[164:167], v[172:175], 0
	v_mfma_i32_16x16x64_i8 v[118:121], v[156:159], v[180:183], 0
	v_mfma_i32_16x16x64_i8 v[114:117], v[164:167], v[180:183], 0
	v_mfma_i32_16x16x64_i8 v[102:105], v[156:159], v[200:203], 0
	v_mfma_i32_16x16x64_i8 v[98:101], v[164:167], v[200:203], 0
	v_mfma_i32_16x16x64_i8 v[84:87], v[156:159], v[208:211], 0
	v_mfma_i32_16x16x64_i8 v[80:83], v[164:167], v[208:211], 0
	v_mfma_i32_16x16x64_i8 v[134:137], v[160:163], v[176:179], v[134:137]
	v_mfma_i32_16x16x64_i8 v[130:133], v[168:171], v[176:179], v[130:133]
	v_mfma_i32_16x16x64_i8 v[118:121], v[160:163], v[190:193], v[118:121]
	v_mfma_i32_16x16x64_i8 v[114:117], v[168:171], v[190:193], v[114:117]
	v_mfma_i32_16x16x64_i8 v[102:105], v[160:163], v[204:207], v[102:105]
	v_mfma_i32_16x16x64_i8 v[98:101], v[168:171], v[204:207], v[98:101]
	v_mfma_i32_16x16x64_i8 v[84:87], v[160:163], v[212:215], v[84:87]
	v_mfma_i32_16x16x64_i8 v[80:83], v[168:171], v[212:215], v[80:83]
	s_setprio 0
	s_barrier
	s_add_i32 s70, s70, s75
	v_lshl_add_u64 v[184:185], s[54:55], 0, v[96:97]
	s_mov_b32 m0, s70
	ds_read_b128 v[172:175], v189 offset:16384
	ds_read_b128 v[176:179], v189 offset:17408
	ds_read_b128 v[180:183], v189 offset:18432
	ds_read_b128 v[190:193], v189 offset:19456
	ds_read_b128 v[200:203], v189 offset:20480
	ds_read_b128 v[204:207], v189 offset:21504
	ds_read_b128 v[208:211], v189 offset:22528
	ds_read_b128 v[212:215], v189 offset:23552
	global_load_lds_dwordx4 v[184:185], off
	s_add_i32 m0, s70, 0x2000
	s_add_u32 s76, s54, 0x80000
	v_lshl_add_u64 v[194:195], s[54:55], 0, v[150:151]
	s_addc_u32 s77, s55, 0
	s_add_i32 s70, s87, s75
	global_load_lds_dwordx4 v[194:195], off
	v_lshl_add_u64 v[216:217], s[76:77], 0, v[96:97]
	s_mov_b32 m0, s70
	v_lshl_add_u64 v[218:219], s[56:57], 0, v[148:149]
	global_load_lds_dwordx4 v[216:217], off
	v_lshl_add_u64 v[216:217], s[76:77], 0, v[150:151]
	s_add_i32 m0, s70, 0x2000
	s_nop 0
	global_load_lds_dwordx4 v[216:217], off
	v_lshl_add_u64 v[216:217], s[56:57], 0, v[146:147]
	s_mov_b32 m0, s80
	s_nop 0
	global_load_lds_dwordx4 v[216:217], off
	s_mov_b32 m0, s85
	s_nop 0
	global_load_lds_dwordx4 v[218:219], off
	s_waitcnt vmcnt(8)
	s_waitcnt lgkmcnt(0)
	s_barrier
; #define PG8_STAGE(bufoff, gbase, voff) do { _Pragma("unroll") for (int _i = 0; _i < 2; ++_i) \
;         __builtin_amdgcn_global_load_lds((const unsigned*)((const char*)(gbase) + (voff)[_i]), (PG8_LAS unsigned*)(lds + (bufoff) + ldsw + _i * 8192), 16, 0, 0); } while (0)
; #define PG8_LDA(dst, b, h) do { _Pragma("unroll") for (int m = 0; m < 4; ++m) _Pragma("unroll") for (int k = 0; k < 2; ++k) dst[m][k] = *(const PG8_LAS bf16x8*)(lds + PG8_SA(b, h) + aoff + m * 2048 + k * 1024); } while (0)
; #define PG8_LDB(dst, b, h) do { _Pragma("unroll") for (int n = 0; n < 2; ++n) _Pragma("unroll") for (int k = 0; k < 2; ++k) dst[n][k] = *(const PG8_LAS bf16x8*)(lds + PG8_SB(b, h) + boff + n * 2048 + k * 1024); } while (0)
; #define PG8_MMA(ai, bj, At, Bt) do { __builtin_amdgcn_s_setprio(1); _Pragma("unroll") for (int m = 0; m < 4; ++m) _Pragma("unroll") for (int n = 0; n < 2; ++n) _Pragma("unroll") for (int k = 0; k < 2; ++k) \
;         mma1<I8>(acc[ai][bj][m][n], Bt[n][k], At[m][k]); __builtin_amdgcn_s_setprio(0); } while (0)
; #define PG8_WAIT_V(n) asm volatile("s_waitcnt vmcnt(" #n ")" ::: "memory")
; #define PG8_WAIT_L(n) asm volatile("s_waitcnt lgkmcnt(" #n ")" ::: "memory")
; #define PG8_BAR __builtin_amdgcn_s_barrier()
; #define PG8_SCHED __builtin_amdgcn_sched_barrier(0)
; template <class Epi, class Sched, bool ALIGN_EPI = false, bool SP2 = false, bool I8 = false>
; __device__ __forceinline__ void gemm_phase(PG8_LAS unsigned char* lds, const Gemm g, const Sched& S, const Epi& E, const int tid) {
;     ...
;             PG8_WAIT_V(8); PG8_WAIT_L(0); PG8_BAR; PG8_MMA(1, 0, At, B0); PG8_MMA(1, 1, At, B1); PG8_BAR; PG8_SCHED;
;             PG8_LDB(B0, 1, 0); PG8_LDB(B1, 1, 1); PG8_SCHED; PG8_LDA(At, 1, 0); PG8_STAGE(PG8_SA(0, 1), a2 + hstepA, voffA);
;             PG8_WAIT_V(8); PG8_WAIT_L(0); PG8_BAR; PG8_MMA(0, 0, At, B0); PG8_MMA(0, 1, At, B1); PG8_BAR; PG8_SCHED;
	s_setprio 1
	s_waitcnt lgkmcnt(0)
	v_mfma_i32_16x16x64_i8 v[76:79], v[48:51], v[172:175], 0
	v_mfma_i32_16x16x64_i8 v[72:75], v[64:67], v[172:175], 0
	v_mfma_i32_16x16x64_i8 v[44:47], v[48:51], v[180:183], 0
	v_mfma_i32_16x16x64_i8 v[40:43], v[64:67], v[180:183], 0
	v_mfma_i32_16x16x64_i8 v[28:31], v[48:51], v[200:203], 0
	v_mfma_i32_16x16x64_i8 v[24:27], v[64:67], v[200:203], 0
	v_mfma_i32_16x16x64_i8 v[12:15], v[48:51], v[208:211], 0
	v_mfma_i32_16x16x64_i8 v[8:11], v[64:67], v[208:211], 0
	v_mfma_i32_16x16x64_i8 v[76:79], v[52:55], v[176:179], v[76:79]
	v_mfma_i32_16x16x64_i8 v[72:75], v[68:71], v[176:179], v[72:75]
	v_mfma_i32_16x16x64_i8 v[44:47], v[52:55], v[190:193], v[44:47]
	v_mfma_i32_16x16x64_i8 v[40:43], v[68:71], v[190:193], v[40:43]
	v_mfma_i32_16x16x64_i8 v[28:31], v[52:55], v[204:207], v[28:31]
	v_mfma_i32_16x16x64_i8 v[24:27], v[68:71], v[204:207], v[24:27]
	v_mfma_i32_16x16x64_i8 v[12:15], v[52:55], v[212:215], v[12:15]
	v_mfma_i32_16x16x64_i8 v[8:11], v[68:71], v[212:215], v[8:11]
	s_setprio 0
	s_setprio 1
	v_mfma_i32_16x16x64_i8 v[36:39], v[156:159], v[180:183], 0
	v_mfma_i32_16x16x64_i8 v[32:35], v[164:167], v[180:183], 0
	v_mfma_i32_16x16x64_i8 v[20:23], v[156:159], v[200:203], 0
	v_mfma_i32_16x16x64_i8 v[16:19], v[164:167], v[200:203], 0
	v_mfma_i32_16x16x64_i8 v[4:7], v[156:159], v[208:211], 0
	v_mfma_i32_16x16x64_i8 v[0:3], v[164:167], v[208:211], 0
	v_mfma_i32_16x16x64_i8 v[48:51], v[156:159], v[172:175], 0
	v_mfma_i32_16x16x64_i8 v[52:55], v[164:167], v[172:175], 0
	v_mfma_i32_16x16x64_i8 v[36:39], v[160:163], v[190:193], v[36:39]
	v_mfma_i32_16x16x64_i8 v[32:35], v[168:171], v[190:193], v[32:35]
	v_mfma_i32_16x16x64_i8 v[20:23], v[160:163], v[204:207], v[20:23]
	v_mfma_i32_16x16x64_i8 v[16:19], v[168:171], v[204:207], v[16:19]
	v_mfma_i32_16x16x64_i8 v[4:7], v[160:163], v[212:215], v[4:7]
	v_mfma_i32_16x16x64_i8 v[0:3], v[168:171], v[212:215], v[0:3]
	v_mfma_i32_16x16x64_i8 v[48:51], v[160:163], v[176:179], v[48:51]
	v_mfma_i32_16x16x64_i8 v[52:55], v[168:171], v[176:179], v[52:55]
	s_setprio 0
	s_barrier
	s_add_i32 s70, 0, 0x18000
	s_add_i32 s76, 0, 0x1c000
	v_add_u32_e32 v68, s70, v187
	v_add_u32_e32 v168, s76, v187
	ds_read_b128 v[56:59], v68
	ds_read_b128 v[60:63], v68 offset:1024
	ds_read_b128 v[64:67], v68 offset:2048
	ds_read_b128 v[68:71], v68 offset:3072
	ds_read_b128 v[156:159], v168
	ds_read_b128 v[160:163], v168 offset:1024
	ds_read_b128 v[164:167], v168 offset:2048
	ds_read_b128 v[168:171], v168 offset:3072
	s_add_u32 s56, s56, 0x80000
	s_addc_u32 s57, s57, 0
	s_mov_b32 m0, s86
	v_lshl_add_u64 v[220:221], s[56:57], 0, v[146:147]
	ds_read_b128 v[172:175], v189 offset:32768
	ds_read_b128 v[176:179], v189 offset:33792
	ds_read_b128 v[180:183], v189 offset:34816
	ds_read_b128 v[190:193], v189 offset:35840
	ds_read_b128 v[200:203], v189 offset:36864
	ds_read_b128 v[204:207], v189 offset:37888
	ds_read_b128 v[208:211], v189 offset:38912
	ds_read_b128 v[212:215], v189 offset:39936
	global_load_lds_dwordx4 v[220:221], off
	v_lshl_add_u64 v[220:221], s[56:57], 0, v[148:149]
	s_mov_b32 m0, s88
	s_nop 0
	global_load_lds_dwordx4 v[220:221], off
	s_waitcnt vmcnt(8)
	s_waitcnt lgkmcnt(0)
	s_barrier
	s_setprio 1
	s_waitcnt lgkmcnt(0)
	v_mfma_i32_16x16x64_i8 v[142:145], v[56:59], v[172:175], v[142:145]
	v_mfma_i32_16x16x64_i8 v[138:141], v[64:67], v[172:175], v[138:141]
	v_mfma_i32_16x16x64_i8 v[126:129], v[56:59], v[180:183], v[126:129]
	v_mfma_i32_16x16x64_i8 v[122:125], v[64:67], v[180:183], v[122:125]
	v_mfma_i32_16x16x64_i8 v[110:113], v[56:59], v[200:203], v[110:113]
	v_mfma_i32_16x16x64_i8 v[106:109], v[64:67], v[200:203], v[106:109]
	v_mfma_i32_16x16x64_i8 v[92:95], v[56:59], v[208:211], v[92:95]
	v_mfma_i32_16x16x64_i8 v[88:91], v[64:67], v[208:211], v[88:91]
	v_mfma_i32_16x16x64_i8 v[142:145], v[60:63], v[176:179], v[142:145]
	v_mfma_i32_16x16x64_i8 v[138:141], v[68:71], v[176:179], v[138:141]
	v_mfma_i32_16x16x64_i8 v[126:129], v[60:63], v[190:193], v[126:129]
	v_mfma_i32_16x16x64_i8 v[122:125], v[68:71], v[190:193], v[122:125]
	v_mfma_i32_16x16x64_i8 v[110:113], v[60:63], v[204:207], v[110:113]
	v_mfma_i32_16x16x64_i8 v[106:109], v[68:71], v[204:207], v[106:109]
	v_mfma_i32_16x16x64_i8 v[92:95], v[60:63], v[212:215], v[92:95]
	v_mfma_i32_16x16x64_i8 v[88:91], v[68:71], v[212:215], v[88:91]
	s_setprio 0
	s_setprio 1
	v_mfma_i32_16x16x64_i8 v[134:137], v[156:159], v[172:175], v[134:137]
	v_mfma_i32_16x16x64_i8 v[130:133], v[164:167], v[172:175], v[130:133]
	v_mfma_i32_16x16x64_i8 v[118:121], v[156:159], v[180:183], v[118:121]
	v_mfma_i32_16x16x64_i8 v[114:117], v[164:167], v[180:183], v[114:117]
	v_mfma_i32_16x16x64_i8 v[102:105], v[156:159], v[200:203], v[102:105]
	v_mfma_i32_16x16x64_i8 v[98:101], v[164:167], v[200:203], v[98:101]
	v_mfma_i32_16x16x64_i8 v[84:87], v[156:159], v[208:211], v[84:87]
	v_mfma_i32_16x16x64_i8 v[80:83], v[164:167], v[208:211], v[80:83]
	v_mfma_i32_16x16x64_i8 v[134:137], v[160:163], v[176:179], v[134:137]
	v_mfma_i32_16x16x64_i8 v[130:133], v[168:171], v[176:179], v[130:133]
	v_mfma_i32_16x16x64_i8 v[118:121], v[160:163], v[190:193], v[118:121]
	v_mfma_i32_16x16x64_i8 v[114:117], v[168:171], v[190:193], v[114:117]
	v_mfma_i32_16x16x64_i8 v[102:105], v[160:163], v[204:207], v[102:105]
	v_mfma_i32_16x16x64_i8 v[98:101], v[168:171], v[204:207], v[98:101]
	v_mfma_i32_16x16x64_i8 v[84:87], v[160:163], v[212:215], v[84:87]
	v_mfma_i32_16x16x64_i8 v[80:83], v[168:171], v[212:215], v[80:83]
	s_setprio 0
	s_barrier
; #define PG8_STAGE(bufoff, gbase, voff) do { _Pragma("unroll") for (int _i = 0; _i < 2; ++_i) \
;         __builtin_amdgcn_global_load_lds((const unsigned*)((const char*)(gbase) + (voff)[_i]), (PG8_LAS unsigned*)(lds + (bufoff) + ldsw + _i * 8192), 16, 0, 0); } while (0)
; #define PG8_LDA(dst, b, h) do { _Pragma("unroll") for (int m = 0; m < 4; ++m) _Pragma("unroll") for (int k = 0; k < 2; ++k) dst[m][k] = *(const PG8_LAS bf16x8*)(lds + PG8_SA(b, h) + aoff + m * 2048 + k * 1024); } while (0)
; #define PG8_MMA(ai, bj, At, Bt) do { __builtin_amdgcn_s_setprio(1); _Pragma("unroll") for (int m = 0; m < 4; ++m) _Pragma("unroll") for (int n = 0; n < 2; ++n) _Pragma("unroll") for (int k = 0; k < 2; ++k) \
;         mma1<I8>(acc[ai][bj][m][n], Bt[n][k], At[m][k]); __builtin_amdgcn_s_setprio(0); } while (0)
; #define PG8_WAIT_V(n) asm volatile("s_waitcnt vmcnt(" #n ")" ::: "memory")
; #define PG8_WAIT_L(n) asm volatile("s_waitcnt lgkmcnt(" #n ")" ::: "memory")
; #define PG8_BAR __builtin_amdgcn_s_barrier()
; #define PG8_SCHED __builtin_amdgcn_sched_barrier(0)
; template <class Epi, class Sched, bool ALIGN_EPI = false, bool SP2 = false, bool I8 = false>
; __device__ __forceinline__ void gemm_phase(PG8_LAS unsigned char* lds, const Gemm g, const Sched& S, const Epi& E, const int tid) {
;     ...
;         for (int t = 0; t < nt; t += 2) {
;     ...
;             PG8_LDA(At, 1, 1); PG8_STAGE(PG8_SB(1, 0), b3, voffB); PG8_STAGE(PG8_SB(1, 1), b3 + hstepB, voffB); PG8_STAGE(PG8_SA(1, 0), a3, voffA);
;             PG8_WAIT_V(8); PG8_WAIT_L(0); PG8_BAR; PG8_MMA(1, 0, At, B0); PG8_MMA(1, 1, At, B1); PG8_BAR; PG8_SCHED;
	s_add_i32 s56, s70, s75
	v_lshl_add_u64 v[184:185], v[184:185], 0, s[42:43]
	s_mov_b32 m0, s56
	ds_read_b128 v[172:175], v189 offset:49152
	ds_read_b128 v[176:179], v189 offset:50176
	ds_read_b128 v[180:183], v189 offset:51200
	ds_read_b128 v[190:193], v189 offset:52224
	ds_read_b128 v[200:203], v189 offset:53248
	ds_read_b128 v[204:207], v189 offset:54272
	ds_read_b128 v[208:211], v189 offset:55296
	ds_read_b128 v[212:215], v189 offset:56320
	global_load_lds_dwordx4 v[184:185], off
	s_add_i32 m0, s56, 0x2000
	s_add_u32 s54, s54, 0x80080
	v_lshl_add_u64 v[184:185], v[194:195], 0, s[42:43]
	s_addc_u32 s55, s55, 0
	s_add_i32 s56, s76, s75
	global_load_lds_dwordx4 v[184:185], off
	v_lshl_add_u64 v[184:185], s[54:55], 0, v[96:97]
	s_mov_b32 m0, s56
	s_nop 0
	global_load_lds_dwordx4 v[184:185], off
	v_lshl_add_u64 v[184:185], s[54:55], 0, v[150:151]
	s_add_i32 m0, s56, 0x2000
	s_nop 0
	global_load_lds_dwordx4 v[184:185], off
	v_lshl_add_u64 v[184:185], v[216:217], 0, s[42:43]
	s_mov_b32 m0, s89
	s_nop 0
	global_load_lds_dwordx4 v[184:185], off
	v_lshl_add_u64 v[184:185], v[218:219], 0, s[42:43]
	s_mov_b32 m0, s90
	s_nop 0
	global_load_lds_dwordx4 v[184:185], off
	s_waitcnt vmcnt(8)
	s_waitcnt lgkmcnt(0)
	s_barrier
	s_setprio 1
	s_waitcnt lgkmcnt(0)
	v_mfma_i32_16x16x64_i8 v[76:79], v[56:59], v[172:175], v[76:79]
	v_mfma_i32_16x16x64_i8 v[72:75], v[64:67], v[172:175], v[72:75]
	v_mfma_i32_16x16x64_i8 v[44:47], v[56:59], v[180:183], v[44:47]
	v_mfma_i32_16x16x64_i8 v[40:43], v[64:67], v[180:183], v[40:43]
	v_mfma_i32_16x16x64_i8 v[28:31], v[56:59], v[200:203], v[28:31]
	v_mfma_i32_16x16x64_i8 v[24:27], v[64:67], v[200:203], v[24:27]
	v_mfma_i32_16x16x64_i8 v[12:15], v[56:59], v[208:211], v[12:15]
	v_mfma_i32_16x16x64_i8 v[8:11], v[64:67], v[208:211], v[8:11]
	v_mfma_i32_16x16x64_i8 v[76:79], v[60:63], v[176:179], v[76:79]
	v_mfma_i32_16x16x64_i8 v[72:75], v[68:71], v[176:179], v[72:75]
	v_mfma_i32_16x16x64_i8 v[44:47], v[60:63], v[190:193], v[44:47]
	v_mfma_i32_16x16x64_i8 v[40:43], v[68:71], v[190:193], v[40:43]
	v_mfma_i32_16x16x64_i8 v[28:31], v[60:63], v[204:207], v[28:31]
	v_mfma_i32_16x16x64_i8 v[24:27], v[68:71], v[204:207], v[24:27]
	v_mfma_i32_16x16x64_i8 v[12:15], v[60:63], v[212:215], v[12:15]
	v_mfma_i32_16x16x64_i8 v[8:11], v[68:71], v[212:215], v[8:11]
	s_setprio 0
	s_setprio 1
	v_mfma_i32_16x16x64_i8 v[48:51], v[156:159], v[172:175], v[48:51]
	v_mfma_i32_16x16x64_i8 v[60:63], v[160:163], v[176:179], v[48:51]
	v_mfma_i32_16x16x64_i8 v[48:51], v[164:167], v[172:175], v[52:55]
	v_mfma_i32_16x16x64_i8 v[36:39], v[156:159], v[180:183], v[36:39]
	v_mfma_i32_16x16x64_i8 v[32:35], v[164:167], v[180:183], v[32:35]
	v_mfma_i32_16x16x64_i8 v[20:23], v[156:159], v[200:203], v[20:23]
	v_mfma_i32_16x16x64_i8 v[16:19], v[164:167], v[200:203], v[16:19]
	v_mfma_i32_16x16x64_i8 v[4:7], v[156:159], v[208:211], v[4:7]
	v_mfma_i32_16x16x64_i8 v[0:3], v[164:167], v[208:211], v[0:3]
	v_mfma_i32_16x16x64_i8 v[56:59], v[168:171], v[176:179], v[48:51]
	v_mfma_i32_16x16x64_i8 v[36:39], v[160:163], v[190:193], v[36:39]
	v_mfma_i32_16x16x64_i8 v[32:35], v[168:171], v[190:193], v[32:35]
	v_mfma_i32_16x16x64_i8 v[20:23], v[160:163], v[204:207], v[20:23]
	v_mfma_i32_16x16x64_i8 v[16:19], v[168:171], v[204:207], v[16:19]
	v_mfma_i32_16x16x64_i8 v[4:7], v[160:163], v[212:215], v[4:7]
	v_mfma_i32_16x16x64_i8 v[0:3], v[168:171], v[212:215], v[0:3]
	s_setprio 0
	s_barrier
	s_add_i32 s65, s65, 2
	s_add_u32 s49, s49, 0x100
	s_addc_u32 s60, s60, 0
	s_add_u32 s46, s46, 0x100
	s_addc_u32 s47, s47, 0
	s_cmp_gt_u32 s65, 29

; #define PG8_STAGE(bufoff, gbase, voff) do { _Pragma("unroll") for (int _i = 0; _i < 2; ++_i) \
;         __builtin_amdgcn_global_load_lds((const unsigned*)((const char*)(gbase) + (voff)[_i]), (PG8_LAS unsigned*)(lds + (bufoff) + ldsw + _i * 8192), 16, 0, 0); } while (0)
; #define PG8_LDA(dst, b, h) do { _Pragma("unroll") for (int m = 0; m < 4; ++m) _Pragma("unroll") for (int k = 0; k < 2; ++k) dst[m][k] = *(const PG8_LAS bf16x8*)(lds + PG8_SA(b, h) + aoff + m * 2048 + k * 1024); } while (0)
; #define PG8_LDB(dst, b, h) do { _Pragma("unroll") for (int n = 0; n < 2; ++n) _Pragma("unroll") for (int k = 0; k < 2; ++k) dst[n][k] = *(const PG8_LAS bf16x8*)(lds + PG8_SB(b, h) + boff + n * 2048 + k * 1024); } while (0)
; template <class Epi, class Sched, bool ALIGN_EPI = false, bool SP2 = false, bool I8 = false>
; __device__ __forceinline__ void gemm_phase(PG8_LAS unsigned char* lds, const Gemm g, const Sched& S, const Epi& E, const int tid) {
;     ...
;         const bool has_next = S.next(ui + 1, nxt);
;         const char* nA = has_next ? (const char*)g.A + (size_t)nxt.pm * tstepA : cA; const char* nB = has_next ? (const char*)g.Bt + (size_t)nxt.pn * tstepB : cB;
;         for (int t = 0; t < nt; t += 2) {
;             const bool last = (t == nt - 2);
;             const char* a1 = cA + (size_t)(t + 1) * kstep;
;             const char* a2 = last ? nA : cA + (size_t)(t + 2) * kstep; const char* b2 = last ? nB : cB + (size_t)(t + 2) * kstep;
;             const char* a3 = a2 + kstep; const char* b3 = b2 + kstep;
;             if (last && has_next) S.a_ready(nxt);
;             if constexpr (SP2) {
;             PG8_LDB(B0, 0, 0); PG8_LDB(B1, 0, 1); PG8_SCHED; PG8_LDA(At, 0, 0); PG8_STAGE(PG8_SA(1, 1), a1 + hstepA, voffA);
;             PG8_WAIT_V(8); PG8_WAIT_L(0); PG8_BAR; PG8_MMA(0, 0, At, B0); PG8_MMA(0, 1, At, B1); PG8_BAR; PG8_SCHED;
;             PG8_LDA(At, 0, 1); PG8_STAGE(PG8_SB(0, 0), b2, voffB); PG8_STAGE(PG8_SB(0, 1), b2 + hstepB, voffB); PG8_STAGE(PG8_SA(0, 0), a2, voffA);
;             PG8_WAIT_V(8); PG8_WAIT_L(0); PG8_BAR; PG8_MMA(1, 0, At, B0); PG8_MMA(1, 1, At, B1); PG8_BAR; PG8_SCHED;
;     ...
;         for (int a = 0; a < 2; ++a)
; #pragma unroll
;             for (int b = 0; b < 2; ++b)
; #pragma unroll
;                 for (int m = 0; m < 4; ++m)
; #pragma unroll
;                     for (int n = 0; n < 2; ++n) acc[a][b][m][n] = AccT<I8>::zero();
.LBB0_939:
	s_ashr_i32 s35, s34, 31
	s_lshl_b64 s[8:9], s[34:35], 20
	s_add_u32 s38, s47, s8
	s_addc_u32 s39, s74, s9
	s_and_b64 s[8:9], s[40:41], exec
	s_cselect_b32 s7, s39, s55
	s_cselect_b32 s35, s38, s54
	s_ashr_i32 s37, s36, 31
	s_lshl_b64 s[8:9], s[36:37], 20
	s_add_u32 s88, s73, s8
	s_addc_u32 s89, s75, s9
	s_and_b64 s[8:9], s[40:41], exec
	s_cselect_b32 s37, s89, s13
	s_cselect_b32 s49, s88, s12
	s_add_u32 s56, s12, 0x100
	s_addc_u32 s57, s13, 0
	s_add_u32 s8, s54, 0x80080
	s_addc_u32 s9, s55, 0
	s_mov_b32 s58, -2
	s_waitcnt vmcnt(0)
	s_add_u32 s12, s8, 0xfff80080
	s_addc_u32 s13, s9, -1
	s_add_i32 s59, 0, 0x10000
	s_cmp_eq_u32 s58, 28
	s_cselect_b32 s55, s7, s13
	s_cselect_b32 s54, s35, s12
	v_add_u32_e32 v96, s59, v225
	s_cselect_b32 s13, s37, s57
	s_cselect_b32 s12, s49, s56
	s_add_i32 s60, 0, 0x14000
	ds_read_b128 v[130:133], v96
	ds_read_b128 v[134:137], v96 offset:1024
	ds_read_b128 v[138:141], v96 offset:2048
	ds_read_b128 v[142:145], v96 offset:3072
	v_add_u32_e32 v96, s60, v225
	ds_read_b128 v[146:149], v96
	ds_read_b128 v[150:153], v96 offset:1024
	ds_read_b128 v[166:169], v96 offset:2048
	ds_read_b128 v[170:173], v96 offset:3072
	v_lshl_add_u64 v[194:195], s[8:9], 0, v[164:165]
	s_add_i32 m0, s3, 0xc000
	ds_read_b128 v[174:177], v226
	ds_read_b128 v[178:181], v226 offset:1024
	ds_read_b128 v[182:185], v226 offset:2048
	ds_read_b128 v[186:189], v226 offset:3072
	ds_read_b128 v[190:193], v226 offset:4096
	ds_read_b128 v[200:203], v226 offset:5120
	ds_read_b128 v[204:207], v226 offset:6144
	ds_read_b128 v[228:231], v226 offset:7168
	global_load_lds_dwordx4 v[194:195], off
	v_lshl_add_u64 v[194:195], s[8:9], 0, v[162:163]
	s_add_i32 m0, s3, 0xe000
	s_nop 0
	global_load_lds_dwordx4 v[194:195], off
	s_waitcnt vmcnt(8)
	s_waitcnt lgkmcnt(0)
	s_barrier
	s_setprio 1
	s_waitcnt lgkmcnt(0)
	v_mfma_i32_16x16x64_i8 v[126:129], v[130:133], v[174:177], 0
	v_mfma_i32_16x16x64_i8 v[122:125], v[138:141], v[174:177], 0
	v_mfma_i32_16x16x64_i8 v[110:113], v[130:133], v[182:185], 0
	v_mfma_i32_16x16x64_i8 v[106:109], v[138:141], v[182:185], 0
	v_mfma_i32_16x16x64_i8 v[92:95], v[130:133], v[190:193], 0
	v_mfma_i32_16x16x64_i8 v[88:91], v[138:141], v[190:193], 0
	v_mfma_i32_16x16x64_i8 v[76:79], v[130:133], v[204:207], 0
	v_mfma_i32_16x16x64_i8 v[72:75], v[138:141], v[204:207], 0
	v_mfma_i32_16x16x64_i8 v[126:129], v[134:137], v[178:181], v[126:129]
	v_mfma_i32_16x16x64_i8 v[122:125], v[142:145], v[178:181], v[122:125]
	v_mfma_i32_16x16x64_i8 v[110:113], v[134:137], v[186:189], v[110:113]
	v_mfma_i32_16x16x64_i8 v[106:109], v[142:145], v[186:189], v[106:109]
	v_mfma_i32_16x16x64_i8 v[92:95], v[134:137], v[200:203], v[92:95]
	v_mfma_i32_16x16x64_i8 v[88:91], v[142:145], v[200:203], v[88:91]
	v_mfma_i32_16x16x64_i8 v[76:79], v[134:137], v[228:231], v[76:79]
	v_mfma_i32_16x16x64_i8 v[72:75], v[142:145], v[228:231], v[72:75]
	s_setprio 0
	s_setprio 1
	v_mfma_i32_16x16x64_i8 v[118:121], v[146:149], v[174:177], 0
	v_mfma_i32_16x16x64_i8 v[114:117], v[166:169], v[174:177], 0
	v_mfma_i32_16x16x64_i8 v[102:105], v[146:149], v[182:185], 0
	v_mfma_i32_16x16x64_i8 v[98:101], v[166:169], v[182:185], 0
	v_mfma_i32_16x16x64_i8 v[84:87], v[146:149], v[190:193], 0
	v_mfma_i32_16x16x64_i8 v[80:83], v[166:169], v[190:193], 0
	v_mfma_i32_16x16x64_i8 v[68:71], v[146:149], v[204:207], 0
	v_mfma_i32_16x16x64_i8 v[64:67], v[166:169], v[204:207], 0
	v_mfma_i32_16x16x64_i8 v[118:121], v[150:153], v[178:181], v[118:121]
	v_mfma_i32_16x16x64_i8 v[114:117], v[170:173], v[178:181], v[114:117]
	v_mfma_i32_16x16x64_i8 v[102:105], v[150:153], v[186:189], v[102:105]
	v_mfma_i32_16x16x64_i8 v[98:101], v[170:173], v[186:189], v[98:101]
	v_mfma_i32_16x16x64_i8 v[84:87], v[150:153], v[200:203], v[84:87]
	v_mfma_i32_16x16x64_i8 v[80:83], v[170:173], v[200:203], v[80:83]
	v_mfma_i32_16x16x64_i8 v[68:71], v[150:153], v[228:231], v[68:71]
	v_mfma_i32_16x16x64_i8 v[64:67], v[170:173], v[228:231], v[64:67]
	s_setprio 0
	s_barrier
	s_add_i32 s59, s59, s1
	v_lshl_add_u64 v[194:195], s[12:13], 0, v[156:157]
	s_mov_b32 m0, s59
	ds_read_b128 v[174:177], v226 offset:16384
	ds_read_b128 v[178:181], v226 offset:17408
	ds_read_b128 v[182:185], v226 offset:18432
	ds_read_b128 v[186:189], v226 offset:19456
	ds_read_b128 v[190:193], v226 offset:20480
	ds_read_b128 v[200:203], v226 offset:21504
	ds_read_b128 v[204:207], v226 offset:22528
	ds_read_b128 v[228:231], v226 offset:23552
	global_load_lds_dwordx4 v[194:195], off
	s_add_i32 m0, s59, 0x2000
	s_add_u32 s76, s12, 0x80000
	v_lshl_add_u64 v[208:209], s[12:13], 0, v[160:161]
	s_addc_u32 s77, s13, 0
	s_add_i32 s59, s60, s1
	global_load_lds_dwordx4 v[208:209], off
	v_lshl_add_u64 v[212:213], s[76:77], 0, v[156:157]
	s_mov_b32 m0, s59
	v_lshl_add_u64 v[216:217], s[54:55], 0, v[158:159]
	global_load_lds_dwordx4 v[212:213], off
	v_lshl_add_u64 v[212:213], s[76:77], 0, v[160:161]
	s_add_i32 m0, s59, 0x2000
	s_nop 0
	global_load_lds_dwordx4 v[212:213], off
	v_lshl_add_u64 v[212:213], s[54:55], 0, v[154:155]
	s_mov_b32 m0, s3
	s_nop 0
	global_load_lds_dwordx4 v[212:213], off
	s_mov_b32 m0, s19
	s_nop 0
	global_load_lds_dwordx4 v[216:217], off
	s_waitcnt vmcnt(8)
	s_waitcnt lgkmcnt(0)
	s_barrier
; #define PG8_STAGE(bufoff, gbase, voff) do { _Pragma("unroll") for (int _i = 0; _i < 2; ++_i) \
;         __builtin_amdgcn_global_load_lds((const unsigned*)((const char*)(gbase) + (voff)[_i]), (PG8_LAS unsigned*)(lds + (bufoff) + ldsw + _i * 8192), 16, 0, 0); } while (0)
; #define PG8_LDA(dst, b, h) do { _Pragma("unroll") for (int m = 0; m < 4; ++m) _Pragma("unroll") for (int k = 0; k < 2; ++k) dst[m][k] = *(const PG8_LAS bf16x8*)(lds + PG8_SA(b, h) + aoff + m * 2048 + k * 1024); } while (0)
; #define PG8_LDB(dst, b, h) do { _Pragma("unroll") for (int n = 0; n < 2; ++n) _Pragma("unroll") for (int k = 0; k < 2; ++k) dst[n][k] = *(const PG8_LAS bf16x8*)(lds + PG8_SB(b, h) + boff + n * 2048 + k * 1024); } while (0)
; #define PG8_MMA(ai, bj, At, Bt) do { __builtin_amdgcn_s_setprio(1); _Pragma("unroll") for (int m = 0; m < 4; ++m) _Pragma("unroll") for (int n = 0; n < 2; ++n) _Pragma("unroll") for (int k = 0; k < 2; ++k) \
;         mma1<I8>(acc[ai][bj][m][n], Bt[n][k], At[m][k]); __builtin_amdgcn_s_setprio(0); } while (0)
; #define PG8_WAIT_V(n) asm volatile("s_waitcnt vmcnt(" #n ")" ::: "memory")
; #define PG8_WAIT_L(n) asm volatile("s_waitcnt lgkmcnt(" #n ")" ::: "memory")
; #define PG8_BAR __builtin_amdgcn_s_barrier()
; #define PG8_SCHED __builtin_amdgcn_sched_barrier(0)
; template <class Epi, class Sched, bool ALIGN_EPI = false, bool SP2 = false, bool I8 = false>
; __device__ __forceinline__ void gemm_phase(PG8_LAS unsigned char* lds, const Gemm g, const Sched& S, const Epi& E, const int tid) {
;     ...
;             PG8_WAIT_V(8); PG8_WAIT_L(0); PG8_BAR; PG8_MMA(1, 0, At, B0); PG8_MMA(1, 1, At, B1); PG8_BAR; PG8_SCHED;
;             PG8_LDB(B0, 1, 0); PG8_LDB(B1, 1, 1); PG8_SCHED; PG8_LDA(At, 1, 0); PG8_STAGE(PG8_SA(0, 1), a2 + hstepA, voffA);
;             PG8_WAIT_V(8); PG8_WAIT_L(0); PG8_BAR; PG8_MMA(0, 0, At, B0); PG8_MMA(0, 1, At, B1); PG8_BAR; PG8_SCHED;
	s_setprio 1
	s_waitcnt lgkmcnt(0)
	v_mfma_i32_16x16x64_i8 v[60:63], v[130:133], v[174:177], 0
	v_mfma_i32_16x16x64_i8 v[56:59], v[138:141], v[174:177], 0
	v_mfma_i32_16x16x64_i8 v[44:47], v[130:133], v[182:185], 0
	v_mfma_i32_16x16x64_i8 v[40:43], v[138:141], v[182:185], 0
	v_mfma_i32_16x16x64_i8 v[28:31], v[130:133], v[190:193], 0
	v_mfma_i32_16x16x64_i8 v[24:27], v[138:141], v[190:193], 0
	v_mfma_i32_16x16x64_i8 v[12:15], v[130:133], v[204:207], 0
	v_mfma_i32_16x16x64_i8 v[8:11], v[138:141], v[204:207], 0
	v_mfma_i32_16x16x64_i8 v[60:63], v[134:137], v[178:181], v[60:63]
	v_mfma_i32_16x16x64_i8 v[56:59], v[142:145], v[178:181], v[56:59]
	v_mfma_i32_16x16x64_i8 v[44:47], v[134:137], v[186:189], v[44:47]
	v_mfma_i32_16x16x64_i8 v[40:43], v[142:145], v[186:189], v[40:43]
	v_mfma_i32_16x16x64_i8 v[28:31], v[134:137], v[200:203], v[28:31]
	v_mfma_i32_16x16x64_i8 v[24:27], v[142:145], v[200:203], v[24:27]
	v_mfma_i32_16x16x64_i8 v[12:15], v[134:137], v[228:231], v[12:15]
	v_mfma_i32_16x16x64_i8 v[8:11], v[142:145], v[228:231], v[8:11]
	s_setprio 0
	s_setprio 1
	v_mfma_i32_16x16x64_i8 v[52:55], v[146:149], v[174:177], 0
	v_mfma_i32_16x16x64_i8 v[48:51], v[166:169], v[174:177], 0
	v_mfma_i32_16x16x64_i8 v[36:39], v[146:149], v[182:185], 0
	v_mfma_i32_16x16x64_i8 v[32:35], v[166:169], v[182:185], 0
	v_mfma_i32_16x16x64_i8 v[20:23], v[146:149], v[190:193], 0
	v_mfma_i32_16x16x64_i8 v[16:19], v[166:169], v[190:193], 0
	v_mfma_i32_16x16x64_i8 v[4:7], v[146:149], v[204:207], 0
	v_mfma_i32_16x16x64_i8 v[0:3], v[166:169], v[204:207], 0
	v_mfma_i32_16x16x64_i8 v[52:55], v[150:153], v[178:181], v[52:55]
	v_mfma_i32_16x16x64_i8 v[48:51], v[170:173], v[178:181], v[48:51]
	v_mfma_i32_16x16x64_i8 v[36:39], v[150:153], v[186:189], v[36:39]
	v_mfma_i32_16x16x64_i8 v[32:35], v[170:173], v[186:189], v[32:35]
	v_mfma_i32_16x16x64_i8 v[20:23], v[150:153], v[200:203], v[20:23]
	v_mfma_i32_16x16x64_i8 v[16:19], v[170:173], v[200:203], v[16:19]
	v_mfma_i32_16x16x64_i8 v[4:7], v[150:153], v[228:231], v[4:7]
	v_mfma_i32_16x16x64_i8 v[0:3], v[170:173], v[228:231], v[0:3]
	s_setprio 0
	s_barrier
	s_add_i32 s59, 0, 0x18000
	v_add_u32_e32 v96, s59, v225
	s_add_i32 s60, 0, 0x1c000
	ds_read_b128 v[130:133], v96
	ds_read_b128 v[134:137], v96 offset:1024
	ds_read_b128 v[138:141], v96 offset:2048
	ds_read_b128 v[142:145], v96 offset:3072
	v_add_u32_e32 v96, s60, v225
	ds_read_b128 v[146:149], v96
	ds_read_b128 v[150:153], v96 offset:1024
	ds_read_b128 v[166:169], v96 offset:2048
	ds_read_b128 v[170:173], v96 offset:3072
	s_add_u32 s54, s54, 0x80000
	s_addc_u32 s55, s55, 0
	s_mov_b32 m0, s48
	v_lshl_add_u64 v[232:233], s[54:55], 0, v[154:155]
	ds_read_b128 v[174:177], v226 offset:32768
	ds_read_b128 v[178:181], v226 offset:33792
	ds_read_b128 v[182:185], v226 offset:34816
	ds_read_b128 v[186:189], v226 offset:35840
	ds_read_b128 v[190:193], v226 offset:36864
	ds_read_b128 v[200:203], v226 offset:37888
	ds_read_b128 v[204:207], v226 offset:38912
	ds_read_b128 v[228:231], v226 offset:39936
	global_load_lds_dwordx4 v[232:233], off
	v_lshl_add_u64 v[232:233], s[54:55], 0, v[158:159]
	s_mov_b32 m0, s51
	s_nop 0
	global_load_lds_dwordx4 v[232:233], off
	s_waitcnt vmcnt(8)
	s_waitcnt lgkmcnt(0)
	s_barrier
	s_setprio 1
	s_waitcnt lgkmcnt(0)
	v_mfma_i32_16x16x64_i8 v[126:129], v[130:133], v[174:177], v[126:129]
	v_mfma_i32_16x16x64_i8 v[122:125], v[138:141], v[174:177], v[122:125]
	v_mfma_i32_16x16x64_i8 v[110:113], v[130:133], v[182:185], v[110:113]
	v_mfma_i32_16x16x64_i8 v[106:109], v[138:141], v[182:185], v[106:109]
	v_mfma_i32_16x16x64_i8 v[92:95], v[130:133], v[190:193], v[92:95]
	v_mfma_i32_16x16x64_i8 v[88:91], v[138:141], v[190:193], v[88:91]
	v_mfma_i32_16x16x64_i8 v[76:79], v[130:133], v[204:207], v[76:79]
	v_mfma_i32_16x16x64_i8 v[72:75], v[138:141], v[204:207], v[72:75]
	v_mfma_i32_16x16x64_i8 v[126:129], v[134:137], v[178:181], v[126:129]
	v_mfma_i32_16x16x64_i8 v[122:125], v[142:145], v[178:181], v[122:125]
	v_mfma_i32_16x16x64_i8 v[110:113], v[134:137], v[186:189], v[110:113]
	v_mfma_i32_16x16x64_i8 v[106:109], v[142:145], v[186:189], v[106:109]
	v_mfma_i32_16x16x64_i8 v[92:95], v[134:137], v[200:203], v[92:95]
	v_mfma_i32_16x16x64_i8 v[88:91], v[142:145], v[200:203], v[88:91]
	v_mfma_i32_16x16x64_i8 v[76:79], v[134:137], v[228:231], v[76:79]
	v_mfma_i32_16x16x64_i8 v[72:75], v[142:145], v[228:231], v[72:75]
	s_setprio 0
	s_setprio 1
	v_mfma_i32_16x16x64_i8 v[118:121], v[146:149], v[174:177], v[118:121]
	v_mfma_i32_16x16x64_i8 v[114:117], v[166:169], v[174:177], v[114:117]
	v_mfma_i32_16x16x64_i8 v[102:105], v[146:149], v[182:185], v[102:105]
	v_mfma_i32_16x16x64_i8 v[98:101], v[166:169], v[182:185], v[98:101]
	v_mfma_i32_16x16x64_i8 v[84:87], v[146:149], v[190:193], v[84:87]
	v_mfma_i32_16x16x64_i8 v[80:83], v[166:169], v[190:193], v[80:83]
	v_mfma_i32_16x16x64_i8 v[68:71], v[146:149], v[204:207], v[68:71]
	v_mfma_i32_16x16x64_i8 v[64:67], v[166:169], v[204:207], v[64:67]
	v_mfma_i32_16x16x64_i8 v[118:121], v[150:153], v[178:181], v[118:121]
	v_mfma_i32_16x16x64_i8 v[114:117], v[170:173], v[178:181], v[114:117]
	v_mfma_i32_16x16x64_i8 v[102:105], v[150:153], v[186:189], v[102:105]
	v_mfma_i32_16x16x64_i8 v[98:101], v[170:173], v[186:189], v[98:101]
	v_mfma_i32_16x16x64_i8 v[84:87], v[150:153], v[200:203], v[84:87]
	v_mfma_i32_16x16x64_i8 v[80:83], v[170:173], v[200:203], v[80:83]
	v_mfma_i32_16x16x64_i8 v[68:71], v[150:153], v[228:231], v[68:71]
	v_mfma_i32_16x16x64_i8 v[64:67], v[170:173], v[228:231], v[64:67]
	s_setprio 0
	s_barrier
; #define PG8_STAGE(bufoff, gbase, voff) do { _Pragma("unroll") for (int _i = 0; _i < 2; ++_i) \
;         __builtin_amdgcn_global_load_lds((const unsigned*)((const char*)(gbase) + (voff)[_i]), (PG8_LAS unsigned*)(lds + (bufoff) + ldsw + _i * 8192), 16, 0, 0); } while (0)
; #define PG8_LDA(dst, b, h) do { _Pragma("unroll") for (int m = 0; m < 4; ++m) _Pragma("unroll") for (int k = 0; k < 2; ++k) dst[m][k] = *(const PG8_LAS bf16x8*)(lds + PG8_SA(b, h) + aoff + m * 2048 + k * 1024); } while (0)
; #define PG8_MMA(ai, bj, At, Bt) do { __builtin_amdgcn_s_setprio(1); _Pragma("unroll") for (int m = 0; m < 4; ++m) _Pragma("unroll") for (int n = 0; n < 2; ++n) _Pragma("unroll") for (int k = 0; k < 2; ++k) \
;         mma1<I8>(acc[ai][bj][m][n], Bt[n][k], At[m][k]); __builtin_amdgcn_s_setprio(0); } while (0)
; #define PG8_WAIT_V(n) asm volatile("s_waitcnt vmcnt(" #n ")" ::: "memory")
; #define PG8_WAIT_L(n) asm volatile("s_waitcnt lgkmcnt(" #n ")" ::: "memory")
; #define PG8_BAR __builtin_amdgcn_s_barrier()
; #define PG8_SCHED __builtin_amdgcn_sched_barrier(0)
; template <class Epi, class Sched, bool ALIGN_EPI = false, bool SP2 = false, bool I8 = false>
; __device__ __forceinline__ void gemm_phase(PG8_LAS unsigned char* lds, const Gemm g, const Sched& S, const Epi& E, const int tid) {
;     ...
;         for (int t = 0; t < nt; t += 2) {
;     ...
;             PG8_LDA(At, 1, 1); PG8_STAGE(PG8_SB(1, 0), b3, voffB); PG8_STAGE(PG8_SB(1, 1), b3 + hstepB, voffB); PG8_STAGE(PG8_SA(1, 0), a3, voffA);
;             PG8_WAIT_V(8); PG8_WAIT_L(0); PG8_BAR; PG8_MMA(1, 0, At, B0); PG8_MMA(1, 1, At, B1); PG8_BAR; PG8_SCHED;
	s_add_i32 s54, s59, s1
	v_lshl_add_u64 v[194:195], v[194:195], 0, s[42:43]
	s_mov_b32 m0, s54
	ds_read_b128 v[174:177], v226 offset:49152
	ds_read_b128 v[178:181], v226 offset:50176
	ds_read_b128 v[182:185], v226 offset:51200
	ds_read_b128 v[186:189], v226 offset:52224
	ds_read_b128 v[190:193], v226 offset:53248
	ds_read_b128 v[200:203], v226 offset:54272
	ds_read_b128 v[204:207], v226 offset:55296
	ds_read_b128 v[228:231], v226 offset:56320
	global_load_lds_dwordx4 v[194:195], off
	s_add_i32 m0, s54, 0x2000
	s_add_u32 s12, s12, 0x80080
	v_lshl_add_u64 v[194:195], v[208:209], 0, s[42:43]
	s_addc_u32 s13, s13, 0
	s_add_i32 s54, s60, s1
	global_load_lds_dwordx4 v[194:195], off
	v_lshl_add_u64 v[194:195], s[12:13], 0, v[156:157]
	s_mov_b32 m0, s54
	s_nop 0
	global_load_lds_dwordx4 v[194:195], off
	v_lshl_add_u64 v[194:195], s[12:13], 0, v[160:161]
	s_add_i32 m0, s54, 0x2000
	s_nop 0
	global_load_lds_dwordx4 v[194:195], off
	v_lshl_add_u64 v[194:195], v[212:213], 0, s[42:43]
	s_mov_b32 m0, s63
	s_nop 0
	global_load_lds_dwordx4 v[194:195], off
	v_lshl_add_u64 v[194:195], v[216:217], 0, s[42:43]
	s_mov_b32 m0, s66
	s_nop 0
	global_load_lds_dwordx4 v[194:195], off
	s_waitcnt vmcnt(8)
	s_waitcnt lgkmcnt(0)
	s_barrier
	s_setprio 1
	s_waitcnt lgkmcnt(0)
	v_mfma_i32_16x16x64_i8 v[60:63], v[130:133], v[174:177], v[60:63]
	v_mfma_i32_16x16x64_i8 v[56:59], v[138:141], v[174:177], v[56:59]
	v_mfma_i32_16x16x64_i8 v[44:47], v[130:133], v[182:185], v[44:47]
	v_mfma_i32_16x16x64_i8 v[40:43], v[138:141], v[182:185], v[40:43]
	v_mfma_i32_16x16x64_i8 v[28:31], v[130:133], v[190:193], v[28:31]
	v_mfma_i32_16x16x64_i8 v[24:27], v[138:141], v[190:193], v[24:27]
	v_mfma_i32_16x16x64_i8 v[12:15], v[130:133], v[204:207], v[12:15]
	v_mfma_i32_16x16x64_i8 v[8:11], v[138:141], v[204:207], v[8:11]
	v_mfma_i32_16x16x64_i8 v[60:63], v[134:137], v[178:181], v[60:63]
	v_mfma_i32_16x16x64_i8 v[56:59], v[142:145], v[178:181], v[56:59]
	v_mfma_i32_16x16x64_i8 v[44:47], v[134:137], v[186:189], v[44:47]
	v_mfma_i32_16x16x64_i8 v[40:43], v[142:145], v[186:189], v[40:43]
	v_mfma_i32_16x16x64_i8 v[28:31], v[134:137], v[200:203], v[28:31]
	v_mfma_i32_16x16x64_i8 v[24:27], v[142:145], v[200:203], v[24:27]
	v_mfma_i32_16x16x64_i8 v[12:15], v[134:137], v[228:231], v[12:15]
	v_mfma_i32_16x16x64_i8 v[8:11], v[142:145], v[228:231], v[8:11]
	s_setprio 0
	s_setprio 1
	v_mfma_i32_16x16x64_i8 v[52:55], v[146:149], v[174:177], v[52:55]
	v_mfma_i32_16x16x64_i8 v[48:51], v[166:169], v[174:177], v[48:51]
	v_mfma_i32_16x16x64_i8 v[36:39], v[146:149], v[182:185], v[36:39]
	v_mfma_i32_16x16x64_i8 v[32:35], v[166:169], v[182:185], v[32:35]
	v_mfma_i32_16x16x64_i8 v[20:23], v[146:149], v[190:193], v[20:23]
	v_mfma_i32_16x16x64_i8 v[16:19], v[166:169], v[190:193], v[16:19]
	v_mfma_i32_16x16x64_i8 v[4:7], v[146:149], v[204:207], v[4:7]
	v_mfma_i32_16x16x64_i8 v[0:3], v[166:169], v[204:207], v[0:3]
	v_mfma_i32_16x16x64_i8 v[52:55], v[150:153], v[178:181], v[52:55]
	v_mfma_i32_16x16x64_i8 v[48:51], v[170:173], v[178:181], v[48:51]
	v_mfma_i32_16x16x64_i8 v[36:39], v[150:153], v[186:189], v[36:39]
	v_mfma_i32_16x16x64_i8 v[32:35], v[170:173], v[186:189], v[32:35]
	v_mfma_i32_16x16x64_i8 v[20:23], v[150:153], v[200:203], v[20:23]
	v_mfma_i32_16x16x64_i8 v[16:19], v[170:173], v[200:203], v[16:19]
	v_mfma_i32_16x16x64_i8 v[4:7], v[150:153], v[228:231], v[4:7]
	v_mfma_i32_16x16x64_i8 v[0:3], v[170:173], v[228:231], v[0:3]
	s_setprio 0
	s_barrier
	s_add_i32 s58, s58, 2
	s_add_u32 s56, s56, 0x100
	s_addc_u32 s57, s57, 0
	s_add_u32 s8, s8, 0x100
	s_addc_u32 s9, s9, 0
	s_cmp_gt_u32 s58, 29

; #define PG8_STAGE(bufoff, gbase, voff) do { _Pragma("unroll") for (int _i = 0; _i < 2; ++_i) \
;         __builtin_amdgcn_global_load_lds((const unsigned*)((const char*)(gbase) + (voff)[_i]), (PG8_LAS unsigned*)(lds + (bufoff) + ldsw + _i * 8192), 16, 0, 0); } while (0)
; #define PG8_LDA(dst, b, h) do { _Pragma("unroll") for (int m = 0; m < 4; ++m) _Pragma("unroll") for (int k = 0; k < 2; ++k) dst[m][k] = *(const PG8_LAS bf16x8*)(lds + PG8_SA(b, h) + aoff + m * 2048 + k * 1024); } while (0)
; #define PG8_LDB(dst, b, h) do { _Pragma("unroll") for (int n = 0; n < 2; ++n) _Pragma("unroll") for (int k = 0; k < 2; ++k) dst[n][k] = *(const PG8_LAS bf16x8*)(lds + PG8_SB(b, h) + boff + n * 2048 + k * 1024); } while (0)
; template <class Epi, class Sched, bool ALIGN_EPI = false, bool SP2 = false, bool I8 = false>
; __device__ __forceinline__ void gemm_phase(PG8_LAS unsigned char* lds, const Gemm g, const Sched& S, const Epi& E, const int tid) {
;     ...
;         const bool has_next = S.next(ui + 1, nxt);
;         const char* nA = has_next ? (const char*)g.A + (size_t)nxt.pm * tstepA : cA; const char* nB = has_next ? (const char*)g.Bt + (size_t)nxt.pn * tstepB : cB;
;         for (int t = 0; t < nt; t += 2) {
;             const bool last = (t == nt - 2);
;             const char* a1 = cA + (size_t)(t + 1) * kstep;
;             const char* a2 = last ? nA : cA + (size_t)(t + 2) * kstep; const char* b2 = last ? nB : cB + (size_t)(t + 2) * kstep;
;             const char* a3 = a2 + kstep; const char* b3 = b2 + kstep;
;             if (last && has_next) S.a_ready(nxt);
;             if constexpr (SP2) {
;             PG8_LDB(B0, 0, 0); PG8_LDB(B1, 0, 1); PG8_SCHED; PG8_LDA(At, 0, 0); PG8_STAGE(PG8_SA(1, 1), a1 + hstepA, voffA);
;             PG8_WAIT_V(8); PG8_WAIT_L(0); PG8_BAR; PG8_MMA(0, 0, At, B0); PG8_MMA(0, 1, At, B1); PG8_BAR; PG8_SCHED;
;             PG8_LDA(At, 0, 1); PG8_STAGE(PG8_SB(0, 0), b2, voffB); PG8_STAGE(PG8_SB(0, 1), b2 + hstepB, voffB); PG8_STAGE(PG8_SA(0, 0), a2, voffA);
;             PG8_WAIT_V(8); PG8_WAIT_L(0); PG8_BAR; PG8_MMA(1, 0, At, B0); PG8_MMA(1, 1, At, B1); PG8_BAR; PG8_SCHED;
;     ...
;         for (int a = 0; a < 2; ++a)
; #pragma unroll
;             for (int b = 0; b < 2; ++b)
; #pragma unroll
;                 for (int m = 0; m < 4; ++m)
; #pragma unroll
;                     for (int n = 0; n < 2; ++n) acc[a][b][m][n] = AccT<I8>::zero();
.LBB0_1008:
	s_ashr_i32 s91, s90, 31
	s_lshl_b64 s[12:13], s[90:91], 20
	s_add_u32 s94, s47, s12
	s_addc_u32 s95, s74, s13
	s_and_b64 s[12:13], s[96:97], exec
	s_cselect_b32 s11, s95, s9
	s_cselect_b32 s14, s94, s8
	s_ashr_i32 s41, s40, 31
	s_lshl_b64 s[12:13], s[40:41], 20
	s_add_u32 s36, s73, s12
	s_addc_u32 s37, s75, s13
	s_and_b64 s[12:13], s[96:97], exec
	s_cselect_b32 s15, s37, s7
	s_cselect_b32 s24, s36, s6
	s_add_u32 s25, s6, 0x100
	s_addc_u32 s41, s7, 0
	s_add_u32 s6, s8, 0x80080
	s_addc_u32 s7, s9, 0
	s_mov_b32 s49, -2
	s_waitcnt vmcnt(0)
	s_add_u32 s8, s6, 0xfff80080
	s_addc_u32 s9, s7, -1
	s_add_i32 s54, 0, 0x10000
	s_cmp_eq_u32 s49, 28
	s_cselect_b32 s13, s11, s9
	s_cselect_b32 s12, s14, s8
	v_add_u32_e32 v96, s54, v243
	s_cselect_b32 s9, s15, s41
	s_cselect_b32 s8, s24, s25
	s_add_i32 s56, 0, 0x14000
	ds_read_b128 v[130:133], v96
	ds_read_b128 v[134:137], v96 offset:1024
	ds_read_b128 v[138:141], v96 offset:2048
	ds_read_b128 v[142:145], v96 offset:3072
	v_add_u32_e32 v96, s56, v243
	ds_read_b128 v[150:153], v96
	ds_read_b128 v[162:165], v96 offset:1024
	ds_read_b128 v[166:169], v96 offset:2048
	ds_read_b128 v[170:173], v96 offset:3072
	v_lshl_add_u64 v[194:195], s[6:7], 0, v[148:149]
	s_add_i32 m0, s93, 0xc000
	ds_read_b128 v[174:177], v244
	ds_read_b128 v[178:181], v244 offset:1024
	ds_read_b128 v[182:185], v244 offset:2048
	ds_read_b128 v[186:189], v244 offset:3072
	ds_read_b128 v[190:193], v244 offset:4096
	ds_read_b128 v[200:203], v244 offset:5120
	ds_read_b128 v[204:207], v244 offset:6144
	ds_read_b128 v[208:211], v244 offset:7168
	global_load_lds_dwordx4 v[194:195], off
	v_lshl_add_u64 v[194:195], s[6:7], 0, v[146:147]
	s_add_i32 m0, s93, 0xe000
	s_nop 0
	global_load_lds_dwordx4 v[194:195], off
	s_waitcnt vmcnt(8)
	s_waitcnt lgkmcnt(0)
	s_barrier
	s_setprio 1
	s_waitcnt lgkmcnt(0)
	v_mfma_i32_16x16x64_i8 v[126:129], v[130:133], v[174:177], 0
	v_mfma_i32_16x16x64_i8 v[122:125], v[138:141], v[174:177], 0
	v_mfma_i32_16x16x64_i8 v[110:113], v[130:133], v[182:185], 0
	v_mfma_i32_16x16x64_i8 v[106:109], v[138:141], v[182:185], 0
	v_mfma_i32_16x16x64_i8 v[92:95], v[130:133], v[190:193], 0
	v_mfma_i32_16x16x64_i8 v[88:91], v[138:141], v[190:193], 0
	v_mfma_i32_16x16x64_i8 v[76:79], v[130:133], v[204:207], 0
	v_mfma_i32_16x16x64_i8 v[72:75], v[138:141], v[204:207], 0
	v_mfma_i32_16x16x64_i8 v[126:129], v[134:137], v[178:181], v[126:129]
	v_mfma_i32_16x16x64_i8 v[122:125], v[142:145], v[178:181], v[122:125]
	v_mfma_i32_16x16x64_i8 v[110:113], v[134:137], v[186:189], v[110:113]
	v_mfma_i32_16x16x64_i8 v[106:109], v[142:145], v[186:189], v[106:109]
	v_mfma_i32_16x16x64_i8 v[92:95], v[134:137], v[200:203], v[92:95]
	v_mfma_i32_16x16x64_i8 v[88:91], v[142:145], v[200:203], v[88:91]
	v_mfma_i32_16x16x64_i8 v[76:79], v[134:137], v[208:211], v[76:79]
	v_mfma_i32_16x16x64_i8 v[72:75], v[142:145], v[208:211], v[72:75]
	s_setprio 0
	s_setprio 1
	v_mfma_i32_16x16x64_i8 v[118:121], v[150:153], v[174:177], 0
	v_mfma_i32_16x16x64_i8 v[114:117], v[166:169], v[174:177], 0
	v_mfma_i32_16x16x64_i8 v[102:105], v[150:153], v[182:185], 0
	v_mfma_i32_16x16x64_i8 v[98:101], v[166:169], v[182:185], 0
	v_mfma_i32_16x16x64_i8 v[84:87], v[150:153], v[190:193], 0
	v_mfma_i32_16x16x64_i8 v[80:83], v[166:169], v[190:193], 0
	v_mfma_i32_16x16x64_i8 v[68:71], v[150:153], v[204:207], 0
	v_mfma_i32_16x16x64_i8 v[64:67], v[166:169], v[204:207], 0
	v_mfma_i32_16x16x64_i8 v[118:121], v[162:165], v[178:181], v[118:121]
	v_mfma_i32_16x16x64_i8 v[114:117], v[170:173], v[178:181], v[114:117]
	v_mfma_i32_16x16x64_i8 v[102:105], v[162:165], v[186:189], v[102:105]
	v_mfma_i32_16x16x64_i8 v[98:101], v[170:173], v[186:189], v[98:101]
	v_mfma_i32_16x16x64_i8 v[84:87], v[162:165], v[200:203], v[84:87]
	v_mfma_i32_16x16x64_i8 v[80:83], v[170:173], v[200:203], v[80:83]
	v_mfma_i32_16x16x64_i8 v[68:71], v[162:165], v[208:211], v[68:71]
	v_mfma_i32_16x16x64_i8 v[64:67], v[170:173], v[208:211], v[64:67]
	s_setprio 0
	s_barrier
	s_add_i32 s54, s54, s19
	v_lshl_add_u64 v[194:195], s[8:9], 0, v[156:157]
	s_mov_b32 m0, s54
	ds_read_b128 v[174:177], v244 offset:16384
	ds_read_b128 v[178:181], v244 offset:17408
	ds_read_b128 v[182:185], v244 offset:18432
	ds_read_b128 v[186:189], v244 offset:19456
	ds_read_b128 v[190:193], v244 offset:20480
	ds_read_b128 v[200:203], v244 offset:21504
	ds_read_b128 v[204:207], v244 offset:22528
	ds_read_b128 v[208:211], v244 offset:23552
	global_load_lds_dwordx4 v[194:195], off
	s_add_i32 m0, s54, 0x2000
	s_add_u32 s54, s8, 0x80000
	v_lshl_add_u64 v[212:213], s[8:9], 0, v[160:161]
	s_addc_u32 s55, s9, 0
	s_add_i32 s56, s56, s19
	global_load_lds_dwordx4 v[212:213], off
	v_lshl_add_u64 v[214:215], s[54:55], 0, v[156:157]
	s_mov_b32 m0, s56
	v_lshl_add_u64 v[216:217], s[12:13], 0, v[158:159]
	global_load_lds_dwordx4 v[214:215], off
	v_lshl_add_u64 v[214:215], s[54:55], 0, v[160:161]
	s_add_i32 m0, s56, 0x2000
	s_nop 0
	global_load_lds_dwordx4 v[214:215], off
	v_lshl_add_u64 v[214:215], s[12:13], 0, v[154:155]
	s_mov_b32 m0, s93
	s_nop 0
	global_load_lds_dwordx4 v[214:215], off
	s_mov_b32 m0, s66
	s_nop 0
	global_load_lds_dwordx4 v[216:217], off
	s_waitcnt vmcnt(8)
	s_waitcnt lgkmcnt(0)
	s_barrier
; #define PG8_STAGE(bufoff, gbase, voff) do { _Pragma("unroll") for (int _i = 0; _i < 2; ++_i) \
;         __builtin_amdgcn_global_load_lds((const unsigned*)((const char*)(gbase) + (voff)[_i]), (PG8_LAS unsigned*)(lds + (bufoff) + ldsw + _i * 8192), 16, 0, 0); } while (0)
; #define PG8_LDA(dst, b, h) do { _Pragma("unroll") for (int m = 0; m < 4; ++m) _Pragma("unroll") for (int k = 0; k < 2; ++k) dst[m][k] = *(const PG8_LAS bf16x8*)(lds + PG8_SA(b, h) + aoff + m * 2048 + k * 1024); } while (0)
; #define PG8_LDB(dst, b, h) do { _Pragma("unroll") for (int n = 0; n < 2; ++n) _Pragma("unroll") for (int k = 0; k < 2; ++k) dst[n][k] = *(const PG8_LAS bf16x8*)(lds + PG8_SB(b, h) + boff + n * 2048 + k * 1024); } while (0)
; #define PG8_MMA(ai, bj, At, Bt) do { __builtin_amdgcn_s_setprio(1); _Pragma("unroll") for (int m = 0; m < 4; ++m) _Pragma("unroll") for (int n = 0; n < 2; ++n) _Pragma("unroll") for (int k = 0; k < 2; ++k) \
;         mma1<I8>(acc[ai][bj][m][n], Bt[n][k], At[m][k]); __builtin_amdgcn_s_setprio(0); } while (0)
; #define PG8_WAIT_V(n) asm volatile("s_waitcnt vmcnt(" #n ")" ::: "memory")
; #define PG8_WAIT_L(n) asm volatile("s_waitcnt lgkmcnt(" #n ")" ::: "memory")
; #define PG8_BAR __builtin_amdgcn_s_barrier()
; #define PG8_SCHED __builtin_amdgcn_sched_barrier(0)
; template <class Epi, class Sched, bool ALIGN_EPI = false, bool SP2 = false, bool I8 = false>
; __device__ __forceinline__ void gemm_phase(PG8_LAS unsigned char* lds, const Gemm g, const Sched& S, const Epi& E, const int tid) {
;     ...
;             PG8_WAIT_V(8); PG8_WAIT_L(0); PG8_BAR; PG8_MMA(1, 0, At, B0); PG8_MMA(1, 1, At, B1); PG8_BAR; PG8_SCHED;
;             PG8_LDB(B0, 1, 0); PG8_LDB(B1, 1, 1); PG8_SCHED; PG8_LDA(At, 1, 0); PG8_STAGE(PG8_SA(0, 1), a2 + hstepA, voffA);
;             PG8_WAIT_V(8); PG8_WAIT_L(0); PG8_BAR; PG8_MMA(0, 0, At, B0); PG8_MMA(0, 1, At, B1); PG8_BAR; PG8_SCHED;
	s_setprio 1
	s_waitcnt lgkmcnt(0)
	v_mfma_i32_16x16x64_i8 v[60:63], v[130:133], v[174:177], 0
	v_mfma_i32_16x16x64_i8 v[56:59], v[138:141], v[174:177], 0
	v_mfma_i32_16x16x64_i8 v[44:47], v[130:133], v[182:185], 0
	v_mfma_i32_16x16x64_i8 v[40:43], v[138:141], v[182:185], 0
	v_mfma_i32_16x16x64_i8 v[28:31], v[130:133], v[190:193], 0
	v_mfma_i32_16x16x64_i8 v[24:27], v[138:141], v[190:193], 0
	v_mfma_i32_16x16x64_i8 v[12:15], v[130:133], v[204:207], 0
	v_mfma_i32_16x16x64_i8 v[8:11], v[138:141], v[204:207], 0
	v_mfma_i32_16x16x64_i8 v[60:63], v[134:137], v[178:181], v[60:63]
	v_mfma_i32_16x16x64_i8 v[56:59], v[142:145], v[178:181], v[56:59]
	v_mfma_i32_16x16x64_i8 v[44:47], v[134:137], v[186:189], v[44:47]
	v_mfma_i32_16x16x64_i8 v[40:43], v[142:145], v[186:189], v[40:43]
	v_mfma_i32_16x16x64_i8 v[28:31], v[134:137], v[200:203], v[28:31]
	v_mfma_i32_16x16x64_i8 v[24:27], v[142:145], v[200:203], v[24:27]
	v_mfma_i32_16x16x64_i8 v[12:15], v[134:137], v[208:211], v[12:15]
	v_mfma_i32_16x16x64_i8 v[8:11], v[142:145], v[208:211], v[8:11]
	s_setprio 0
	s_setprio 1
	v_mfma_i32_16x16x64_i8 v[52:55], v[150:153], v[174:177], 0
	v_mfma_i32_16x16x64_i8 v[48:51], v[166:169], v[174:177], 0
	v_mfma_i32_16x16x64_i8 v[36:39], v[150:153], v[182:185], 0
	v_mfma_i32_16x16x64_i8 v[32:35], v[166:169], v[182:185], 0
	v_mfma_i32_16x16x64_i8 v[20:23], v[150:153], v[190:193], 0
	v_mfma_i32_16x16x64_i8 v[16:19], v[166:169], v[190:193], 0
	v_mfma_i32_16x16x64_i8 v[4:7], v[150:153], v[204:207], 0
	v_mfma_i32_16x16x64_i8 v[0:3], v[166:169], v[204:207], 0
	v_mfma_i32_16x16x64_i8 v[52:55], v[162:165], v[178:181], v[52:55]
	v_mfma_i32_16x16x64_i8 v[48:51], v[170:173], v[178:181], v[48:51]
	v_mfma_i32_16x16x64_i8 v[36:39], v[162:165], v[186:189], v[36:39]
	v_mfma_i32_16x16x64_i8 v[32:35], v[170:173], v[186:189], v[32:35]
	v_mfma_i32_16x16x64_i8 v[20:23], v[162:165], v[200:203], v[20:23]
	v_mfma_i32_16x16x64_i8 v[16:19], v[170:173], v[200:203], v[16:19]
	v_mfma_i32_16x16x64_i8 v[4:7], v[162:165], v[208:211], v[4:7]
	v_mfma_i32_16x16x64_i8 v[0:3], v[170:173], v[208:211], v[0:3]
	s_setprio 0
	s_barrier
	s_add_i32 s54, 0, 0x18000
	v_add_u32_e32 v96, s54, v243
	s_add_i32 s55, 0, 0x1c000
	ds_read_b128 v[130:133], v96
	ds_read_b128 v[134:137], v96 offset:1024
	ds_read_b128 v[138:141], v96 offset:2048
	ds_read_b128 v[142:145], v96 offset:3072
	v_add_u32_e32 v96, s55, v243
	ds_read_b128 v[150:153], v96
	ds_read_b128 v[162:165], v96 offset:1024
	ds_read_b128 v[166:169], v96 offset:2048
	ds_read_b128 v[170:173], v96 offset:3072
	s_add_u32 s12, s12, 0x80000
	s_addc_u32 s13, s13, 0
	s_mov_b32 m0, s1
	v_lshl_add_u64 v[218:219], s[12:13], 0, v[154:155]
	ds_read_b128 v[174:177], v244 offset:32768
	ds_read_b128 v[178:181], v244 offset:33792
	ds_read_b128 v[182:185], v244 offset:34816
	ds_read_b128 v[186:189], v244 offset:35840
	ds_read_b128 v[190:193], v244 offset:36864
	ds_read_b128 v[200:203], v244 offset:37888
	ds_read_b128 v[204:207], v244 offset:38912
	ds_read_b128 v[208:211], v244 offset:39936
	global_load_lds_dwordx4 v[218:219], off
	v_lshl_add_u64 v[218:219], s[12:13], 0, v[158:159]
	s_mov_b32 m0, s52
	s_nop 0
	global_load_lds_dwordx4 v[218:219], off
	s_waitcnt vmcnt(8)
	s_waitcnt lgkmcnt(0)
	s_barrier
	s_setprio 1
	s_waitcnt lgkmcnt(0)
	v_mfma_i32_16x16x64_i8 v[126:129], v[130:133], v[174:177], v[126:129]
	v_mfma_i32_16x16x64_i8 v[122:125], v[138:141], v[174:177], v[122:125]
	v_mfma_i32_16x16x64_i8 v[110:113], v[130:133], v[182:185], v[110:113]
	v_mfma_i32_16x16x64_i8 v[106:109], v[138:141], v[182:185], v[106:109]
	v_mfma_i32_16x16x64_i8 v[92:95], v[130:133], v[190:193], v[92:95]
	v_mfma_i32_16x16x64_i8 v[88:91], v[138:141], v[190:193], v[88:91]
	v_mfma_i32_16x16x64_i8 v[76:79], v[130:133], v[204:207], v[76:79]
	v_mfma_i32_16x16x64_i8 v[72:75], v[138:141], v[204:207], v[72:75]
	v_mfma_i32_16x16x64_i8 v[126:129], v[134:137], v[178:181], v[126:129]
	v_mfma_i32_16x16x64_i8 v[122:125], v[142:145], v[178:181], v[122:125]
	v_mfma_i32_16x16x64_i8 v[110:113], v[134:137], v[186:189], v[110:113]
	v_mfma_i32_16x16x64_i8 v[106:109], v[142:145], v[186:189], v[106:109]
	v_mfma_i32_16x16x64_i8 v[92:95], v[134:137], v[200:203], v[92:95]
	v_mfma_i32_16x16x64_i8 v[88:91], v[142:145], v[200:203], v[88:91]
	v_mfma_i32_16x16x64_i8 v[76:79], v[134:137], v[208:211], v[76:79]
	v_mfma_i32_16x16x64_i8 v[72:75], v[142:145], v[208:211], v[72:75]
	s_setprio 0
	s_setprio 1
	v_mfma_i32_16x16x64_i8 v[118:121], v[150:153], v[174:177], v[118:121]
	v_mfma_i32_16x16x64_i8 v[114:117], v[166:169], v[174:177], v[114:117]
	v_mfma_i32_16x16x64_i8 v[102:105], v[150:153], v[182:185], v[102:105]
	v_mfma_i32_16x16x64_i8 v[98:101], v[166:169], v[182:185], v[98:101]
	v_mfma_i32_16x16x64_i8 v[84:87], v[150:153], v[190:193], v[84:87]
	v_mfma_i32_16x16x64_i8 v[80:83], v[166:169], v[190:193], v[80:83]
	v_mfma_i32_16x16x64_i8 v[68:71], v[150:153], v[204:207], v[68:71]
	v_mfma_i32_16x16x64_i8 v[64:67], v[166:169], v[204:207], v[64:67]
	v_mfma_i32_16x16x64_i8 v[118:121], v[162:165], v[178:181], v[118:121]
	v_mfma_i32_16x16x64_i8 v[114:117], v[170:173], v[178:181], v[114:117]
	v_mfma_i32_16x16x64_i8 v[102:105], v[162:165], v[186:189], v[102:105]
	v_mfma_i32_16x16x64_i8 v[98:101], v[170:173], v[186:189], v[98:101]
	v_mfma_i32_16x16x64_i8 v[84:87], v[162:165], v[200:203], v[84:87]
	v_mfma_i32_16x16x64_i8 v[80:83], v[170:173], v[200:203], v[80:83]
	v_mfma_i32_16x16x64_i8 v[68:71], v[162:165], v[208:211], v[68:71]
	v_mfma_i32_16x16x64_i8 v[64:67], v[170:173], v[208:211], v[64:67]
	s_setprio 0
	s_barrier
; #define PG8_STAGE(bufoff, gbase, voff) do { _Pragma("unroll") for (int _i = 0; _i < 2; ++_i) \
;         __builtin_amdgcn_global_load_lds((const unsigned*)((const char*)(gbase) + (voff)[_i]), (PG8_LAS unsigned*)(lds + (bufoff) + ldsw + _i * 8192), 16, 0, 0); } while (0)
; #define PG8_LDA(dst, b, h) do { _Pragma("unroll") for (int m = 0; m < 4; ++m) _Pragma("unroll") for (int k = 0; k < 2; ++k) dst[m][k] = *(const PG8_LAS bf16x8*)(lds + PG8_SA(b, h) + aoff + m * 2048 + k * 1024); } while (0)
; #define PG8_MMA(ai, bj, At, Bt) do { __builtin_amdgcn_s_setprio(1); _Pragma("unroll") for (int m = 0; m < 4; ++m) _Pragma("unroll") for (int n = 0; n < 2; ++n) _Pragma("unroll") for (int k = 0; k < 2; ++k) \
;         mma1<I8>(acc[ai][bj][m][n], Bt[n][k], At[m][k]); __builtin_amdgcn_s_setprio(0); } while (0)
; #define PG8_WAIT_V(n) asm volatile("s_waitcnt vmcnt(" #n ")" ::: "memory")
; #define PG8_WAIT_L(n) asm volatile("s_waitcnt lgkmcnt(" #n ")" ::: "memory")
; #define PG8_BAR __builtin_amdgcn_s_barrier()
; #define PG8_SCHED __builtin_amdgcn_sched_barrier(0)
; template <class Epi, class Sched, bool ALIGN_EPI = false, bool SP2 = false, bool I8 = false>
; __device__ __forceinline__ void gemm_phase(PG8_LAS unsigned char* lds, const Gemm g, const Sched& S, const Epi& E, const int tid) {
;     ...
;         for (int t = 0; t < nt; t += 2) {
;     ...
;             PG8_LDA(At, 1, 1); PG8_STAGE(PG8_SB(1, 0), b3, voffB); PG8_STAGE(PG8_SB(1, 1), b3 + hstepB, voffB); PG8_STAGE(PG8_SA(1, 0), a3, voffA);
;             PG8_WAIT_V(8); PG8_WAIT_L(0); PG8_BAR; PG8_MMA(1, 0, At, B0); PG8_MMA(1, 1, At, B1); PG8_BAR; PG8_SCHED;
	s_add_i32 s12, s54, s19
	v_lshl_add_u64 v[194:195], v[194:195], 0, s[42:43]
	s_mov_b32 m0, s12
	ds_read_b128 v[174:177], v244 offset:49152
	ds_read_b128 v[178:181], v244 offset:50176
	ds_read_b128 v[182:185], v244 offset:51200
	ds_read_b128 v[186:189], v244 offset:52224
	ds_read_b128 v[190:193], v244 offset:53248
	ds_read_b128 v[200:203], v244 offset:54272
	ds_read_b128 v[204:207], v244 offset:55296
	ds_read_b128 v[208:211], v244 offset:56320
	global_load_lds_dwordx4 v[194:195], off
	s_add_i32 m0, s12, 0x2000
	s_add_u32 s8, s8, 0x80080
	v_lshl_add_u64 v[194:195], v[212:213], 0, s[42:43]
	s_addc_u32 s9, s9, 0
	s_add_i32 s12, s55, s19
	global_load_lds_dwordx4 v[194:195], off
	v_lshl_add_u64 v[194:195], s[8:9], 0, v[156:157]
	s_mov_b32 m0, s12
	s_nop 0
	global_load_lds_dwordx4 v[194:195], off
	v_lshl_add_u64 v[194:195], s[8:9], 0, v[160:161]
	s_add_i32 m0, s12, 0x2000
	s_nop 0
	global_load_lds_dwordx4 v[194:195], off
	v_lshl_add_u64 v[194:195], v[214:215], 0, s[42:43]
	s_mov_b32 m0, s63
	s_nop 0
	global_load_lds_dwordx4 v[194:195], off
	v_lshl_add_u64 v[194:195], v[216:217], 0, s[42:43]
	s_mov_b32 m0, s86
	s_nop 0
	global_load_lds_dwordx4 v[194:195], off
	s_waitcnt vmcnt(8)
	s_waitcnt lgkmcnt(0)
	s_barrier
	s_setprio 1
	s_waitcnt lgkmcnt(0)
	v_mfma_i32_16x16x64_i8 v[60:63], v[130:133], v[174:177], v[60:63]
	v_mfma_i32_16x16x64_i8 v[56:59], v[138:141], v[174:177], v[56:59]
	v_mfma_i32_16x16x64_i8 v[44:47], v[130:133], v[182:185], v[44:47]
	v_mfma_i32_16x16x64_i8 v[40:43], v[138:141], v[182:185], v[40:43]
	v_mfma_i32_16x16x64_i8 v[28:31], v[130:133], v[190:193], v[28:31]
	v_mfma_i32_16x16x64_i8 v[24:27], v[138:141], v[190:193], v[24:27]
	v_mfma_i32_16x16x64_i8 v[12:15], v[130:133], v[204:207], v[12:15]
	v_mfma_i32_16x16x64_i8 v[8:11], v[138:141], v[204:207], v[8:11]
	v_mfma_i32_16x16x64_i8 v[60:63], v[134:137], v[178:181], v[60:63]
	v_mfma_i32_16x16x64_i8 v[56:59], v[142:145], v[178:181], v[56:59]
	v_mfma_i32_16x16x64_i8 v[44:47], v[134:137], v[186:189], v[44:47]
	v_mfma_i32_16x16x64_i8 v[40:43], v[142:145], v[186:189], v[40:43]
	v_mfma_i32_16x16x64_i8 v[28:31], v[134:137], v[200:203], v[28:31]
	v_mfma_i32_16x16x64_i8 v[24:27], v[142:145], v[200:203], v[24:27]
	v_mfma_i32_16x16x64_i8 v[12:15], v[134:137], v[208:211], v[12:15]
	v_mfma_i32_16x16x64_i8 v[8:11], v[142:145], v[208:211], v[8:11]
	s_setprio 0
	s_setprio 1
	v_mfma_i32_16x16x64_i8 v[52:55], v[150:153], v[174:177], v[52:55]
	v_mfma_i32_16x16x64_i8 v[48:51], v[166:169], v[174:177], v[48:51]
	v_mfma_i32_16x16x64_i8 v[36:39], v[150:153], v[182:185], v[36:39]
	v_mfma_i32_16x16x64_i8 v[32:35], v[166:169], v[182:185], v[32:35]
	v_mfma_i32_16x16x64_i8 v[20:23], v[150:153], v[190:193], v[20:23]
	v_mfma_i32_16x16x64_i8 v[16:19], v[166:169], v[190:193], v[16:19]
	v_mfma_i32_16x16x64_i8 v[4:7], v[150:153], v[204:207], v[4:7]
	v_mfma_i32_16x16x64_i8 v[0:3], v[166:169], v[204:207], v[0:3]
	v_mfma_i32_16x16x64_i8 v[52:55], v[162:165], v[178:181], v[52:55]
	v_mfma_i32_16x16x64_i8 v[48:51], v[170:173], v[178:181], v[48:51]
	v_mfma_i32_16x16x64_i8 v[36:39], v[162:165], v[186:189], v[36:39]
	v_mfma_i32_16x16x64_i8 v[32:35], v[170:173], v[186:189], v[32:35]
	v_mfma_i32_16x16x64_i8 v[20:23], v[162:165], v[200:203], v[20:23]
	v_mfma_i32_16x16x64_i8 v[16:19], v[170:173], v[200:203], v[16:19]
	v_mfma_i32_16x16x64_i8 v[4:7], v[162:165], v[208:211], v[4:7]
	v_mfma_i32_16x16x64_i8 v[0:3], v[170:173], v[208:211], v[0:3]
	s_setprio 0
	s_barrier
	s_add_i32 s49, s49, 2
	s_add_u32 s25, s25, 0x100
	s_addc_u32 s41, s41, 0
	s_add_u32 s6, s6, 0x100
	s_addc_u32 s7, s7, 0
	s_cmp_gt_u32 s49, 29
